# speedup vs baseline: 1.0304x; 1.0037x over previous
; DEVI bf16_t f2bf(float x) { return (bf16_t)(cvtpk(x, x) & 0xffffu); }
; DEVI void lru_coef_phase(const Params& p, char* lds) {
;     ...
;       for (int t = 0; t < 16; ++t) {
;         const float xp1 = ld(rs + t + 1);
;         const float v = w0 * xm2 + w1 * xm1 + w2 * x0 + w3 * xp1 + cb;
;         const int lr = rg * 16 + t;
;         XR[lr * 128 + c] = v;
;         *(bf16_t*)(AT + lr * 256 + ((((c >> 3) ^ (lr & 15)) << 4) | ((c & 7) << 1))) = f2bf(v);
;         xm2 = xm1; xm1 = x0; x0 = xp1;
;       }
;     }
;     __syncthreads();
.Llcoef_b:
	s_waitcnt vmcnt(0)
	v_lshlrev_b32_e32 v20, 16, v20
	v_lshlrev_b32_e32 v21, 16, v21
	v_lshlrev_b32_e32 v22, 16, v22
	v_lshlrev_b32_e32 v23, 16, v23
	v_lshlrev_b32_e32 v24, 16, v24
	v_lshlrev_b32_e32 v25, 16, v25
	v_lshlrev_b32_e32 v26, 16, v26
	v_lshlrev_b32_e32 v27, 16, v27
	v_lshlrev_b32_e32 v28, 16, v28
	v_lshlrev_b32_e32 v29, 16, v29
	v_lshlrev_b32_e32 v30, 16, v30
	v_lshlrev_b32_e32 v31, 16, v31
	v_lshlrev_b32_e32 v32, 16, v32
	v_lshlrev_b32_e32 v33, 16, v33
	v_lshlrev_b32_e32 v34, 16, v34
	v_lshlrev_b32_e32 v35, 16, v35
	v_lshlrev_b32_e32 v36, 16, v36
	v_lshlrev_b32_e32 v37, 16, v37
	v_lshlrev_b32_e32 v38, 16, v38
	v_mul_f32_e32 v3, v9, v21
	v_fmac_f32_e32 v3, v8, v20
	v_fmac_f32_e32 v3, v10, v22
	v_fmac_f32_e32 v3, v11, v23
	v_add_f32_e32 v3, v0, v3
	ds_write_b32 v123, v3
	v_cvt_pk_bf16_f32 v3, v3, v3
	ds_write_b16 v124, v3 offset:32768
	v_mul_f32_e32 v3, v9, v22
	v_fmac_f32_e32 v3, v8, v21
	v_fmac_f32_e32 v3, v10, v23
	v_fmac_f32_e32 v3, v11, v24
	v_add_f32_e32 v3, v0, v3
	ds_write_b32 v125, v3
	v_cvt_pk_bf16_f32 v3, v3, v3
	ds_write_b16 v126, v3 offset:32768
	v_mul_f32_e32 v3, v9, v23
	v_fmac_f32_e32 v3, v8, v22
	v_fmac_f32_e32 v3, v10, v24
	v_fmac_f32_e32 v3, v11, v25
	v_add_f32_e32 v3, v0, v3
	ds_write_b32 v127, v3
	v_cvt_pk_bf16_f32 v3, v3, v3
	ds_write_b16 v128, v3 offset:32768
	v_mul_f32_e32 v3, v9, v24
	v_fmac_f32_e32 v3, v8, v23
	v_fmac_f32_e32 v3, v10, v25
	v_fmac_f32_e32 v3, v11, v26
	v_add_f32_e32 v3, v0, v3
	ds_write_b32 v129, v3
	v_cvt_pk_bf16_f32 v3, v3, v3
	ds_write_b16 v130, v3 offset:32768
	v_mul_f32_e32 v3, v9, v25
	v_fmac_f32_e32 v3, v8, v24
	v_fmac_f32_e32 v3, v10, v26
	v_fmac_f32_e32 v3, v11, v27
	v_add_f32_e32 v3, v0, v3
	ds_write_b32 v131, v3
	v_cvt_pk_bf16_f32 v3, v3, v3
	ds_write_b16 v132, v3 offset:32768
	v_mul_f32_e32 v3, v9, v26
	v_fmac_f32_e32 v3, v8, v25
	v_fmac_f32_e32 v3, v10, v27
	v_fmac_f32_e32 v3, v11, v28
	v_add_f32_e32 v3, v0, v3
	ds_write_b32 v133, v3
	v_cvt_pk_bf16_f32 v3, v3, v3
	ds_write_b16 v134, v3 offset:32768
	v_mul_f32_e32 v3, v9, v27
	v_fmac_f32_e32 v3, v8, v26
	v_fmac_f32_e32 v3, v10, v28
	v_fmac_f32_e32 v3, v11, v29
	v_add_f32_e32 v3, v0, v3
	ds_write_b32 v135, v3
	v_cvt_pk_bf16_f32 v3, v3, v3
	ds_write_b16 v136, v3 offset:32768
	v_mul_f32_e32 v3, v9, v28
	v_fmac_f32_e32 v3, v8, v27
	v_fmac_f32_e32 v3, v10, v29
	v_fmac_f32_e32 v3, v11, v30
	v_add_f32_e32 v3, v0, v3
	ds_write_b32 v137, v3
	v_cvt_pk_bf16_f32 v3, v3, v3
	ds_write_b16 v138, v3 offset:32768
	v_mul_f32_e32 v3, v9, v29
	v_fmac_f32_e32 v3, v8, v28
	v_fmac_f32_e32 v3, v10, v30
	v_fmac_f32_e32 v3, v11, v31
	v_add_f32_e32 v3, v0, v3
	ds_write_b32 v139, v3
	v_cvt_pk_bf16_f32 v3, v3, v3
	ds_write_b16 v140, v3 offset:32768
	v_mul_f32_e32 v3, v9, v30
	v_fmac_f32_e32 v3, v8, v29
	v_fmac_f32_e32 v3, v10, v31
	v_fmac_f32_e32 v3, v11, v32
	v_add_f32_e32 v3, v0, v3
	ds_write_b32 v141, v3
	v_cvt_pk_bf16_f32 v3, v3, v3
	ds_write_b16 v142, v3 offset:32768
	v_mul_f32_e32 v3, v9, v31
	v_fmac_f32_e32 v3, v8, v30
	v_fmac_f32_e32 v3, v10, v32
	v_fmac_f32_e32 v3, v11, v33
	v_add_f32_e32 v3, v0, v3
	ds_write_b32 v143, v3
	v_cvt_pk_bf16_f32 v3, v3, v3
	ds_write_b16 v144, v3 offset:32768
	v_mul_f32_e32 v3, v9, v32
	v_fmac_f32_e32 v3, v8, v31
	v_fmac_f32_e32 v3, v10, v33
	v_fmac_f32_e32 v3, v11, v34
	v_add_f32_e32 v3, v0, v3
	ds_write_b32 v145, v3
	v_cvt_pk_bf16_f32 v3, v3, v3
	ds_write_b16 v146, v3 offset:32768
	v_mul_f32_e32 v3, v9, v33
	v_fmac_f32_e32 v3, v8, v32
	v_fmac_f32_e32 v3, v10, v34
	v_fmac_f32_e32 v3, v11, v35
	v_add_f32_e32 v3, v0, v3
	ds_write_b32 v147, v3
	v_cvt_pk_bf16_f32 v3, v3, v3
	ds_write_b16 v148, v3 offset:32768
	v_mul_f32_e32 v3, v9, v34
	v_fmac_f32_e32 v3, v8, v33
	v_fmac_f32_e32 v3, v10, v35
	v_fmac_f32_e32 v3, v11, v36
	v_add_f32_e32 v3, v0, v3
	ds_write_b32 v149, v3
	v_cvt_pk_bf16_f32 v3, v3, v3
	ds_write_b16 v150, v3 offset:32768
	v_mul_f32_e32 v3, v9, v35
	v_fmac_f32_e32 v3, v8, v34
	v_fmac_f32_e32 v3, v10, v36
	v_fmac_f32_e32 v3, v11, v37
	v_add_f32_e32 v3, v0, v3
	ds_write_b32 v151, v3
	v_cvt_pk_bf16_f32 v3, v3, v3
	ds_write_b16 v152, v3 offset:32768
	v_mul_f32_e32 v3, v9, v36
	v_fmac_f32_e32 v3, v8, v35
	v_fmac_f32_e32 v3, v10, v37
	v_fmac_f32_e32 v3, v11, v38
	v_add_f32_e32 v3, v0, v3
	ds_write_b32 v153, v3
	v_cvt_pk_bf16_f32 v3, v3, v3
	ds_write_b16 v154, v3 offset:32768
	v_readlane_b32 s61, v255, 11
	v_readlane_b32 s66, v255, 16
	v_readlane_b32 s67, v255, 17
	v_readlane_b32 s68, v255, 18
	v_readlane_b32 s69, v255, 19
	v_readlane_b32 s70, v255, 20
	v_readlane_b32 s71, v255, 21
	v_readlane_b32 s72, v255, 22
	v_readlane_b32 s73, v255, 23
	v_readlane_b32 s74, v255, 24
	v_readlane_b32 s75, v255, 25
	v_or_b32_e32 v2, s1, v119
	v_ashrrev_i32_e32 v3, 31, v2
	v_lshlrev_b64 v[2:3], 15, v[2:3]
	v_lshl_or_b32 v2, v82, 1, v2
	v_lshl_add_u64 v[98:99], v[66:67], 0, v[2:3]
	s_waitcnt lgkmcnt(0)
	s_barrier
; DEVI void lru_coef_phase(const Params& p, char* lds) {
;     ...
;     const bf16_t* wr = WT + WT_LRG + ((size_t)(dir * 8 + blk) * 128 + chh * 64 + r32) * 128 + hi * 8;
;     const bf16_t* wg = WT + WT_LIG + ((size_t)(dir * 8 + blk) * 128 + chh * 64 + r32) * 128 + hi * 8;
; #pragma unroll
;     for (int s = 0; s < 8; ++s) {
;       const int lr = rb * 32 + r32;
;       const bf16x8 af = *(const bf16x8*)(AT + lr * 256 + (((s * 2 + hi) ^ (lr & 15)) << 4));
; #pragma unroll
;       for (int nb = 0; nb < 2; ++nb) {
;         const bf16x8 b1 = *(const bf16x8*)(wr + nb * 32 * 128 + s * 16);
;         const bf16x8 b2 = *(const bf16x8*)(wg + nb * 32 * 128 + s * 16);
;         ar[nb] = __builtin_amdgcn_mfma_f32_32x32x16_bf16(af, b1, ar[nb], 0, 0, 0);
;         ai[nb] = __builtin_amdgcn_mfma_f32_32x32x16_bf16(af, b2, ai[nb], 0, 0, 0);
;       }
;     }
	v_lshl_add_u64 v[100:101], v[68:69], 0, v[2:3]
	ds_read_b128 v[86:89], v155 offset:32768
	global_load_dwordx4 v[90:93], v[98:99], off
	global_load_dwordx4 v[94:97], v[100:101], off
	v_add_co_u32_e32 v102, vcc, s52, v98
	s_nop 1
	v_addc_co_u32_e32 v103, vcc, 0, v99, vcc
	v_add_co_u32_e32 v104, vcc, s52, v100
	s_nop 1
	v_addc_co_u32_e32 v105, vcc, 0, v101, vcc
	global_load_dwordx4 v[186:189], v[102:103], off
	global_load_dwordx4 v[190:193], v[104:105], off
	global_load_dwordx4 v[194:197], v[98:99], off offset:32
	global_load_dwordx4 v[198:201], v[100:101], off offset:32
	global_load_dwordx4 v[202:205], v[102:103], off offset:32
	global_load_dwordx4 v[206:209], v[104:105], off offset:32
	global_load_dwordx4 v[210:213], v[98:99], off offset:64
	global_load_dwordx4 v[240:243], v[100:101], off offset:64
	global_load_dwordx4 v[244:247], v[102:103], off offset:64
	global_load_dwordx4 v[248:251], v[104:105], off offset:64
	v_or_b32_e32 v116, s0, v121
	v_ashrrev_i32_e32 v117, 31, v116
	v_readlane_b32 s60, v255, 10
	v_readlane_b32 s61, v255, 11
	v_readlane_b32 s62, v255, 12
	v_readlane_b32 s63, v255, 13
	v_readlane_b32 s64, v255, 14
	v_readlane_b32 s65, v255, 15
	v_readlane_b32 s66, v255, 16
	v_readlane_b32 s67, v255, 17
	v_readlane_b32 s68, v255, 18
	v_readlane_b32 s69, v255, 19
	v_readlane_b32 s70, v255, 20
	v_readlane_b32 s71, v255, 21
	v_readlane_b32 s72, v255, 22
	v_readlane_b32 s73, v255, 23
	v_readlane_b32 s74, v255, 24
	v_readlane_b32 s75, v255, 25
	ds_read_b128 v[106:109], v156 offset:32768
	s_waitcnt vmcnt(8) lgkmcnt(1)
	v_mfma_f32_32x32x16_bf16 v[50:65], v[86:89], v[90:93], 0
	v_mfma_f32_32x32x16_bf16 v[18:33], v[86:89], v[94:97], 0
	v_mfma_f32_32x32x16_bf16 v[34:49], v[86:89], v[186:189], 0
	v_mfma_f32_32x32x16_bf16 v[2:17], v[86:89], v[190:193], 0
	global_load_dwordx4 v[90:93], v[98:99], off offset:96
	global_load_dwordx4 v[94:97], v[100:101], off offset:96
	global_load_dwordx4 v[186:189], v[102:103], off offset:96
	global_load_dwordx4 v[190:193], v[104:105], off offset:96
	ds_read_b128 v[86:89], v157 offset:32768
	s_waitcnt vmcnt(8) lgkmcnt(1)
	v_mfma_f32_32x32x16_bf16 v[50:65], v[106:109], v[194:197], v[50:65]
	v_mfma_f32_32x32x16_bf16 v[18:33], v[106:109], v[198:201], v[18:33]
	v_mfma_f32_32x32x16_bf16 v[34:49], v[106:109], v[202:205], v[34:49]
	v_mfma_f32_32x32x16_bf16 v[2:17], v[106:109], v[206:209], v[2:17]
	global_load_dwordx4 v[194:197], v[98:99], off offset:128
	global_load_dwordx4 v[198:201], v[100:101], off offset:128
	global_load_dwordx4 v[202:205], v[102:103], off offset:128
	global_load_dwordx4 v[206:209], v[104:105], off offset:128
	ds_read_b128 v[106:109], v158 offset:32768
	s_waitcnt vmcnt(8) lgkmcnt(1)
	v_mfma_f32_32x32x16_bf16 v[50:65], v[86:89], v[210:213], v[50:65]
	v_mfma_f32_32x32x16_bf16 v[18:33], v[86:89], v[240:243], v[18:33]
	v_mfma_f32_32x32x16_bf16 v[34:49], v[86:89], v[244:247], v[34:49]
	v_mfma_f32_32x32x16_bf16 v[2:17], v[86:89], v[248:251], v[2:17]
	global_load_dwordx4 v[210:213], v[98:99], off offset:160
	global_load_dwordx4 v[240:243], v[100:101], off offset:160
	global_load_dwordx4 v[244:247], v[102:103], off offset:160
	global_load_dwordx4 v[248:251], v[104:105], off offset:160
	ds_read_b128 v[86:89], v159 offset:32768
	s_waitcnt vmcnt(8) lgkmcnt(1)
	v_mfma_f32_32x32x16_bf16 v[50:65], v[106:109], v[90:93], v[50:65]
	v_mfma_f32_32x32x16_bf16 v[18:33], v[106:109], v[94:97], v[18:33]
	v_mfma_f32_32x32x16_bf16 v[34:49], v[106:109], v[186:189], v[34:49]
	v_mfma_f32_32x32x16_bf16 v[2:17], v[106:109], v[190:193], v[2:17]
	global_load_dwordx4 v[90:93], v[98:99], off offset:192
	global_load_dwordx4 v[94:97], v[100:101], off offset:192
	global_load_dwordx4 v[186:189], v[102:103], off offset:192
	global_load_dwordx4 v[190:193], v[104:105], off offset:192
	ds_read_b128 v[106:109], v160 offset:32768
	s_waitcnt vmcnt(8) lgkmcnt(1)
	v_mfma_f32_32x32x16_bf16 v[50:65], v[86:89], v[194:197], v[50:65]
	v_mfma_f32_32x32x16_bf16 v[18:33], v[86:89], v[198:201], v[18:33]
	v_mfma_f32_32x32x16_bf16 v[34:49], v[86:89], v[202:205], v[34:49]
	v_mfma_f32_32x32x16_bf16 v[2:17], v[86:89], v[206:209], v[2:17]
	global_load_dwordx4 v[194:197], v[98:99], off offset:224
	global_load_dwordx4 v[198:201], v[100:101], off offset:224
	global_load_dwordx4 v[202:205], v[102:103], off offset:224
	global_load_dwordx4 v[206:209], v[104:105], off offset:224
	ds_read_b128 v[86:89], v161 offset:32768
	s_waitcnt vmcnt(8) lgkmcnt(1)
	v_mfma_f32_32x32x16_bf16 v[50:65], v[106:109], v[210:213], v[50:65]
	v_mfma_f32_32x32x16_bf16 v[18:33], v[106:109], v[240:243], v[18:33]
	v_mfma_f32_32x32x16_bf16 v[34:49], v[106:109], v[244:247], v[34:49]
	v_mfma_f32_32x32x16_bf16 v[2:17], v[106:109], v[248:251], v[2:17]
	ds_read_b128 v[106:109], v162 offset:32768
	s_waitcnt vmcnt(4) lgkmcnt(1)
	v_mfma_f32_32x32x16_bf16 v[50:65], v[86:89], v[90:93], v[50:65]
	v_mfma_f32_32x32x16_bf16 v[18:33], v[86:89], v[94:97], v[18:33]
	v_mfma_f32_32x32x16_bf16 v[34:49], v[86:89], v[186:189], v[34:49]
	v_mfma_f32_32x32x16_bf16 v[2:17], v[86:89], v[190:193], v[2:17]
	ds_read2_b32 v[112:113], v122 offset1:32
	ds_read2_b32 v[114:115], v122 offset0:128 offset1:160
	s_waitcnt vmcnt(0) lgkmcnt(2)
	v_mfma_f32_32x32x16_bf16 v[50:65], v[106:109], v[194:197], v[50:65]
	v_mfma_f32_32x32x16_bf16 v[18:33], v[106:109], v[198:201], v[18:33]
	v_mfma_f32_32x32x16_bf16 v[34:49], v[106:109], v[202:205], v[34:49]
	v_mfma_f32_32x32x16_bf16 v[2:17], v[106:109], v[206:209], v[2:17]
	v_or_b32_e32 v86, v116, v70
	v_ashrrev_i32_e32 v87, 31, v86
	v_lshlrev_b64 v[86:87], 2, v[86:87]
	v_lshl_add_u64 v[88:89], s[68:69], 0, v[86:87]
	global_load_dword v169, v[88:89], off
	v_lshl_add_u64 v[88:89], s[72:73], 0, v[86:87]
	v_lshl_add_u64 v[86:87], s[74:75], 0, v[86:87]
	global_load_dword v0, v[86:87], off
	global_load_dword v168, v[88:89], off
	v_lshl_add_u64 v[116:117], v[116:117], 0, v[70:71]
	v_lshlrev_b64 v[170:171], 2, v[116:117]
	v_lshl_add_u64 v[116:117], s[68:69], 0, v[170:171]
	v_lshl_add_u64 v[172:173], s[72:73], 0, v[170:171]
	v_lshl_add_u64 v[170:171], s[74:75], 0, v[170:171]
	s_waitcnt vmcnt(1)
; DEVI float sigmoidf_(float x) { return __builtin_amdgcn_rcpf(1.f + __expf(-x)); }
; DEVI int crow(int r, int hi) { return (r & 3) + 8 * (r >> 2) + 4 * hi; }
; DEVI void lru_coef_phase(const Params& p, char* lds) {
;     ...
;       const float brg = p.in[I_LBRG][dir * 1024 + ch], big = p.in[I_LBIG][dir * 1024 + ch];
;       const float sp = log1pf(__expf(-p.in[I_LLAM][dir * 1024 + ch]));
; #pragma unroll
;       for (int r = 0; r < 16; ++r) {
;         const int lr = rb * 32 + crow(r, hi);
;         const float xr = XR[lr * 128 + col];
;         const float rg_ = sigmoidf_(ar[nb][r] + brg), ig_ = sigmoidf_(ai[nb][r] + big);
;         const float la = -8.f * rg_ * sp;
;         tla[nb][r] = la;
;         const float x2 = 2.f * la;
;         const float om = -x2 * fmaf(x2, fmaf(x2, fmaf(x2, fmaf(x2, 1.f / 120.f, 1.f / 24.f), 1.f / 6.f), 0.5f), 1.f);
;         tbb[nb][r] = __builtin_amdgcn_sqrtf(fmaxf(om, 0.f)) * ig_ * xr;
;       }
;     }
;     {
;       bf16_t* d1 = LA + ((size_t)dir * MT + r0 + rb * 32) * 1024; bf16_t* d2 = BB + ((size_t)dir * MT + r0 + rb * 32) * 1024;
;       char* slice = lds + 49152 + w * 4096;
;       store2_bf16(tla[0], tla[1], slice, lane, blk * 128 + chh * 64, [=](int rr) { return d1 + (size_t)rr * 1024; });
;       store2_bf16(tbb[0], tbb[1], slice, lane, blk * 128 + chh * 64, [=](int rr) { return d2 + (size_t)rr * 1024; });
	v_mul_f32_e32 v0, 0xbfb8aa3b, v0
	v_exp_f32_e32 v0, v0
	s_nop 0
	v_add_f32_e32 v85, 1.0, v0
	v_add_f32_e32 v86, -1.0, v85
	v_sub_f32_e32 v87, v86, v85
	v_add_f32_e32 v87, 1.0, v87
	v_sub_f32_e32 v86, v0, v86
	v_add_f32_e32 v88, v86, v87
	v_frexp_mant_f32_e32 v86, v85
	v_cmp_gt_f32_e32 vcc, s54, v86
	v_cvt_f64_f32_e32 v[86:87], v85
	v_frexp_exp_i32_f64_e32 v86, v[86:87]
	v_subbrev_co_u32_e32 v86, vcc, 0, v86, vcc
	v_sub_u32_e32 v87, 0, v86
	v_ldexp_f32 v85, v85, v87
	v_ldexp_f32 v87, v88, v87
	v_add_f32_e32 v88, -1.0, v85
	v_add_f32_e32 v89, 1.0, v88
	v_sub_f32_e32 v89, v85, v89
	v_add_f32_e32 v89, v87, v89
	v_add_f32_e32 v90, v88, v89
	v_sub_f32_e32 v88, v90, v88
	v_sub_f32_e32 v88, v89, v88
	v_add_f32_e32 v89, 1.0, v85
	v_add_f32_e32 v91, -1.0, v89
	v_sub_f32_e32 v85, v85, v91
	v_add_f32_e32 v85, v87, v85
	v_add_f32_e32 v87, v89, v85
	v_sub_f32_e32 v89, v87, v89
	v_sub_f32_e32 v85, v85, v89
	v_rcp_f32_e32 v89, v87
	v_cvt_f32_i32_e32 v86, v86
	v_cmp_neq_f32_e32 vcc, s53, v0
	v_mul_f32_e32 v91, v90, v89
	v_mul_f32_e32 v92, v87, v91
	v_fma_f32 v93, v91, v87, -v92
	v_fmac_f32_e32 v93, v91, v85
	v_add_f32_e32 v94, v92, v93
	v_sub_f32_e32 v95, v90, v94
	v_sub_f32_e32 v90, v90, v95
	v_sub_f32_e32 v92, v94, v92
	v_sub_f32_e32 v90, v90, v94
	v_add_f32_e32 v88, v88, v90
	v_sub_f32_e32 v90, v92, v93
	v_add_f32_e32 v88, v90, v88
	v_add_f32_e32 v90, v95, v88
	v_mul_f32_e32 v92, v89, v90
	v_mul_f32_e32 v93, v87, v92
	v_fma_f32 v87, v92, v87, -v93
	v_fmac_f32_e32 v87, v92, v85
	v_sub_f32_e32 v85, v95, v90
	v_add_f32_e32 v85, v88, v85
	v_add_f32_e32 v88, v93, v87
	v_sub_f32_e32 v94, v90, v88
	v_sub_f32_e32 v90, v90, v94
	v_sub_f32_e32 v93, v88, v93
	v_sub_f32_e32 v88, v90, v88
	v_add_f32_e32 v85, v85, v88
	v_sub_f32_e32 v87, v93, v87
	v_add_f32_e32 v85, v87, v85
	v_add_f32_e32 v87, v91, v92
	v_add_f32_e32 v85, v94, v85
	v_sub_f32_e32 v88, v87, v91
	v_mul_f32_e32 v85, v89, v85
	v_sub_f32_e32 v88, v92, v88
	v_add_f32_e32 v85, v88, v85
	v_mul_f32_e32 v91, 0x3f317218, v86
	v_add_f32_e32 v88, v87, v85
	v_fma_f32 v92, v86, s55, -v91
	v_mul_f32_e32 v89, v88, v88
	v_fmac_f32_e32 v92, 0xb102e308, v86
	v_sub_f32_e32 v86, v88, v87
	v_fmamk_f32 v90, v89, 0x3e9b6dac, v218
	v_sub_f32_e32 v85, v85, v86
	v_add_f32_e32 v86, v91, v92
	v_fmaak_f32 v90, v89, v90, 0x3f2aaada
	v_sub_f32_e32 v87, v86, v91
	v_ldexp_f32 v91, v88, 1
	v_mul_f32_e32 v88, v88, v89
	v_mul_f32_e32 v88, v88, v90
	v_add_f32_e32 v89, v91, v88
	v_sub_f32_e32 v90, v89, v91
	v_ldexp_f32 v85, v85, 1
	v_sub_f32_e32 v88, v88, v90
	v_add_f32_e32 v85, v85, v88
	v_add_f32_e32 v88, v89, v85
	v_sub_f32_e32 v89, v88, v89
	v_sub_f32_e32 v85, v85, v89
	v_add_f32_e32 v89, v86, v88
	v_sub_f32_e32 v90, v89, v86
	v_sub_f32_e32 v91, v89, v90
	v_sub_f32_e32 v87, v92, v87
	v_sub_f32_e32 v86, v86, v91
	v_sub_f32_e32 v88, v88, v90
	v_add_f32_e32 v86, v88, v86
	v_add_f32_e32 v88, v87, v85
	v_sub_f32_e32 v90, v88, v87
	v_sub_f32_e32 v91, v88, v90
	v_sub_f32_e32 v87, v87, v91
	v_sub_f32_e32 v85, v85, v90
	v_add_f32_e32 v86, v88, v86
	v_add_f32_e32 v85, v85, v87
	v_add_f32_e32 v87, v89, v86
	v_sub_f32_e32 v88, v87, v89
	v_sub_f32_e32 v86, v86, v88
	v_add_f32_e32 v85, v85, v86
	v_add_f32_e32 v85, v87, v85
	v_cndmask_b32_e32 v85, v224, v85, vcc
	v_cmp_ngt_f32_e32 vcc, -1.0, v0
	s_nop 1
	v_cndmask_b32_e32 v85, v228, v85, vcc
	v_cmp_neq_f32_e32 vcc, -1.0, v0
	s_nop 1
	v_cndmask_b32_e32 v85, v229, v85, vcc
	v_cmp_lt_f32_e64 vcc, |v0|, s56
	s_nop 1
	v_cndmask_b32_e32 v180, v85, v0, vcc
	v_add_f32_e32 v0, v50, v169
	v_mul_f32_e32 v0, 0xbfb8aa3b, v0
	v_exp_f32_e32 v0, v0
	v_add_u32_e32 v50, 0x400, v122
	ds_read2_b32 v[110:111], v50 offset1:32
	ds_read2_b32 v[108:109], v50 offset0:128 offset1:160
	v_add_u32_e32 v50, 0x1000, v122
	v_add_f32_e32 v0, 1.0, v0
	v_rcp_f32_e32 v0, v0
	ds_read2_b32 v[106:107], v50 offset1:32
	ds_read2_b32 v[104:105], v50 offset0:128 offset1:160
	v_add_u32_e32 v50, 0x1400, v122
	ds_read2_b32 v[102:103], v50 offset1:32
	ds_read2_b32 v[100:101], v50 offset0:128 offset1:160
	v_add_u32_e32 v50, 0x2000, v122
	ds_read2_b32 v[98:99], v50 offset1:32
	ds_read2_b32 v[96:97], v50 offset0:128 offset1:160
	v_add_u32_e32 v50, 0x2400, v122
	ds_read2_b32 v[94:95], v50 offset1:32
	ds_read2_b32 v[92:93], v50 offset0:128 offset1:160
	v_add_u32_e32 v50, 0x3000, v122
	v_mul_f32_e32 v0, 0xc1000000, v0
	ds_read2_b32 v[90:91], v50 offset1:32
	ds_read2_b32 v[88:89], v50 offset0:128 offset1:160
	v_add_u32_e32 v50, 0x3400, v122
	v_mul_f32_e32 v85, v0, v180
	v_add_f32_e32 v0, v51, v169
	ds_read2_b32 v[86:87], v50 offset1:32
	ds_read2_b32 v[50:51], v50 offset0:128 offset1:160
	global_load_dword v117, v[116:117], off offset:128
	v_mul_f32_e32 v0, 0xbfb8aa3b, v0
	global_load_dword v116, v[172:173], off offset:128
	global_load_dword v181, v[170:171], off offset:128
	v_exp_f32_e32 v0, v0
	s_nop 0
	v_add_f32_e32 v0, 1.0, v0
	v_rcp_f32_e32 v0, v0
	s_nop 0
	v_mul_f32_e32 v0, 0xc1000000, v0
	v_mul_f32_e32 v0, v0, v180
	v_cndmask_b32_e64 v171, v85, v0, s[38:39]
	s_nop 1
	v_mov_b32_dpp v171, v171 quad_perm:[1,0,3,2] row_mask:0xf bank_mask:0xf
	s_and_saveexec_b64 s[22:23], s[40:41]
	s_xor_b64 s[22:23], exec, s[22:23]
	s_cbranch_execz .LBB0_1193
	v_cvt_pk_bf16_f32 v170, v171, v0

; DEVI void s5_out_phase(const Params& p) {
;     ...
; #pragma unroll 8
;     for (int s = 0; s < 16; ++s) {
;       const bf16x8 af = *(const bf16x8*)(ua + (size_t)s * 512);
; #pragma unroll
;       for (int nb = 0; nb < 2; ++nb) {
;         const bf16x8 bfr = *(const bf16x8*)(mb + (size_t)nb * 32 * 512 + s * 16);
;         acc[nb] = __builtin_amdgcn_mfma_f32_32x32x16_bf16(af, bfr, acc[nb], 0, 0, 0);
;       }
;     }
.LBB0_1848:
	s_waitcnt vmcnt(0)
	v_lshl_add_u64 v[54:55], v[50:51], 0, v[36:37]
	v_lshl_add_u64 v[74:75], v[52:53], 0, v[36:37]
	v_add_co_u32_e32 v72, vcc, s2, v54
	s_nop 1
	v_addc_co_u32_e32 v73, vcc, 0, v55, vcc
	v_add_co_u32_e32 v54, vcc, s3, v54
	s_nop 1
	v_addc_co_u32_e32 v55, vcc, 0, v55, vcc
	v_add_co_u32_e32 v56, vcc, 0xecd8000, v74
	s_nop 1
	v_addc_co_u32_e32 v57, vcc, 0, v75, vcc
	v_add_co_u32_e32 v74, vcc, 0xece0000, v74
	s_nop 1
	v_addc_co_u32_e32 v75, vcc, 0, v75, vcc
	global_load_dwordx4 v[180:183], v[72:73], off
	global_load_dwordx4 v[92:95], v[56:57], off
	global_load_dwordx4 v[124:127], v[74:75], off
	global_load_dwordx4 v[184:187], v[72:73], off offset:1024
	global_load_dwordx4 v[96:99], v[56:57], off offset:32
	global_load_dwordx4 v[128:131], v[74:75], off offset:32
	global_load_dwordx4 v[188:191], v[72:73], off offset:2048
	global_load_dwordx4 v[100:103], v[56:57], off offset:64
	global_load_dwordx4 v[132:135], v[74:75], off offset:64
	global_load_dwordx4 v[192:195], v[72:73], off offset:3072
	global_load_dwordx4 v[104:107], v[56:57], off offset:96
	global_load_dwordx4 v[136:139], v[74:75], off offset:96
	global_load_dwordx4 v[196:199], v[54:55], off
	global_load_dwordx4 v[108:111], v[56:57], off offset:128
	global_load_dwordx4 v[140:143], v[74:75], off offset:128
	global_load_dwordx4 v[200:203], v[54:55], off offset:1024
	global_load_dwordx4 v[112:115], v[56:57], off offset:160
	global_load_dwordx4 v[144:147], v[74:75], off offset:160
	global_load_dwordx4 v[204:207], v[54:55], off offset:2048
	global_load_dwordx4 v[116:119], v[56:57], off offset:192
	global_load_dwordx4 v[148:151], v[74:75], off offset:192
	global_load_dwordx4 v[208:211], v[54:55], off offset:3072
	global_load_dwordx4 v[120:123], v[56:57], off offset:224
	global_load_dwordx4 v[152:155], v[74:75], off offset:224
	v_lshl_add_u64 v[50:51], v[50:51], 0, s[76:77]
	v_lshl_add_u64 v[52:53], v[52:53], 0, s[82:83]
	s_add_i32 s0, s0, -8
	s_cmp_lg_u32 s0, 0
	s_waitcnt vmcnt(21)
	v_mfma_f32_32x32x16_bf16 v[18:33], v[180:183], v[92:95], v[18:33]
	v_mfma_f32_32x32x16_bf16 v[2:17], v[180:183], v[124:127], v[2:17]
	s_waitcnt vmcnt(18)
	v_mfma_f32_32x32x16_bf16 v[18:33], v[184:187], v[96:99], v[18:33]
	v_mfma_f32_32x32x16_bf16 v[2:17], v[184:187], v[128:131], v[2:17]
	s_waitcnt vmcnt(15)
	v_mfma_f32_32x32x16_bf16 v[18:33], v[188:191], v[100:103], v[18:33]
	v_mfma_f32_32x32x16_bf16 v[2:17], v[188:191], v[132:135], v[2:17]
	s_waitcnt vmcnt(12)
	v_mfma_f32_32x32x16_bf16 v[18:33], v[192:195], v[104:107], v[18:33]
	v_mfma_f32_32x32x16_bf16 v[2:17], v[192:195], v[136:139], v[2:17]
	s_waitcnt vmcnt(9)
	v_mfma_f32_32x32x16_bf16 v[18:33], v[196:199], v[108:111], v[18:33]
	v_mfma_f32_32x32x16_bf16 v[2:17], v[196:199], v[140:143], v[2:17]
	s_waitcnt vmcnt(6)
	v_mfma_f32_32x32x16_bf16 v[18:33], v[200:203], v[112:115], v[18:33]
	v_mfma_f32_32x32x16_bf16 v[2:17], v[200:203], v[144:147], v[2:17]
	s_waitcnt vmcnt(3)
	v_mfma_f32_32x32x16_bf16 v[18:33], v[204:207], v[116:119], v[18:33]
	v_mfma_f32_32x32x16_bf16 v[2:17], v[204:207], v[148:151], v[2:17]
	s_waitcnt vmcnt(0)
	v_mfma_f32_32x32x16_bf16 v[18:33], v[208:211], v[120:123], v[18:33]
	v_mfma_f32_32x32x16_bf16 v[2:17], v[208:211], v[152:155], v[2:17]
	s_cbranch_scc1 .LBB0_1848
	v_mul_hi_i32_i24_e32 v47, 0x820, v46
	v_mul_i32_i24_e32 v46, 0x820, v46
	v_ashrrev_i32_e32 v45, 31, v44
	v_lshl_add_u64 v[44:45], v[46:47], 0, v[44:45]
	v_lshlrev_b64 v[46:47], 9, v[44:45]
	v_lshl_add_u64 v[44:45], v[38:39], 0, v[48:49]
	v_lshl_add_u64 v[46:47], v[40:41], 0, v[46:47]
	s_mov_b64 s[2:3], 0
; DEVI float geluf_(float x) { return 0.5f * x * (1.f + erff(x * 0.70710678118654752f)); }
; DEVI void s5_out_phase(const Params& p) {
;     ...
; #pragma unroll 8
;     for (int s = 0; s < 16; ++s) {
;       const bf16x8 af = *(const bf16x8*)(sa + s * 16);
; #pragma unroll
;       for (int nb = 0; nb < 2; ++nb) {
;         const bf16x8 bfr = *(const bf16x8*)(mb + (size_t)nb * 32 * 512 + 256 + s * 16);
;         acc[nb] = __builtin_amdgcn_mfma_f32_32x32x16_bf16(af, bfr, acc[nb], 0, 0, 0);
;       }
;     }
; #pragma unroll
;     for (int nb = 0; nb < 2; ++nb) {
;       f32x16 t;
; #pragma unroll
;       for (int r = 0; r < 16; ++r) t[r] = geluf_(acc[nb][r]);
.LBB0_1850:
	s_waitcnt vmcnt(0)
	v_lshl_add_u64 v[56:57], v[46:47], 0, s[2:3]
	v_lshl_add_u64 v[48:49], v[44:45], 0, s[2:3]
	v_add_co_u32_e32 v50, vcc, 0xecd8000, v48
	s_nop 1
	v_addc_co_u32_e32 v51, vcc, 0, v49, vcc
	v_add_co_u32_e32 v48, vcc, 0xece0000, v48
	s_nop 1
	v_addc_co_u32_e32 v49, vcc, 0, v49, vcc
	global_load_dwordx4 v[180:183], v[56:57], off offset:-128
	global_load_dwordx4 v[92:95], v[50:51], off offset:512
	global_load_dwordx4 v[124:127], v[48:49], off offset:512
	global_load_dwordx4 v[184:187], v[56:57], off offset:-96
	global_load_dwordx4 v[96:99], v[50:51], off offset:544
	global_load_dwordx4 v[128:131], v[48:49], off offset:544
	global_load_dwordx4 v[188:191], v[56:57], off offset:-64
	global_load_dwordx4 v[100:103], v[50:51], off offset:576
	global_load_dwordx4 v[132:135], v[48:49], off offset:576
	global_load_dwordx4 v[192:195], v[56:57], off offset:-32
	global_load_dwordx4 v[104:107], v[50:51], off offset:608
	global_load_dwordx4 v[136:139], v[48:49], off offset:608
	global_load_dwordx4 v[196:199], v[56:57], off
	global_load_dwordx4 v[108:111], v[50:51], off offset:640
	global_load_dwordx4 v[140:143], v[48:49], off offset:640
	global_load_dwordx4 v[200:203], v[56:57], off offset:32
	global_load_dwordx4 v[112:115], v[50:51], off offset:672
	global_load_dwordx4 v[144:147], v[48:49], off offset:672
	global_load_dwordx4 v[204:207], v[56:57], off offset:64
	global_load_dwordx4 v[116:119], v[50:51], off offset:704
	global_load_dwordx4 v[148:151], v[48:49], off offset:704
	global_load_dwordx4 v[208:211], v[56:57], off offset:96
	global_load_dwordx4 v[120:123], v[50:51], off offset:736
	global_load_dwordx4 v[152:155], v[48:49], off offset:736
	s_add_u32 s2, s2, 0x100
	s_addc_u32 s3, s3, 0
	s_cmpk_eq_i32 s2, 0x200
	s_waitcnt vmcnt(21)
	v_mfma_f32_32x32x16_bf16 v[18:33], v[180:183], v[92:95], v[18:33]
	v_mfma_f32_32x32x16_bf16 v[2:17], v[180:183], v[124:127], v[2:17]
	s_waitcnt vmcnt(18)
	v_mfma_f32_32x32x16_bf16 v[18:33], v[184:187], v[96:99], v[18:33]
	v_mfma_f32_32x32x16_bf16 v[2:17], v[184:187], v[128:131], v[2:17]
	s_waitcnt vmcnt(15)
	v_mfma_f32_32x32x16_bf16 v[18:33], v[188:191], v[100:103], v[18:33]
	v_mfma_f32_32x32x16_bf16 v[2:17], v[188:191], v[132:135], v[2:17]
	s_waitcnt vmcnt(12)
	v_mfma_f32_32x32x16_bf16 v[18:33], v[192:195], v[104:107], v[18:33]
	v_mfma_f32_32x32x16_bf16 v[2:17], v[192:195], v[136:139], v[2:17]
	s_waitcnt vmcnt(9)
	v_mfma_f32_32x32x16_bf16 v[18:33], v[196:199], v[108:111], v[18:33]
	v_mfma_f32_32x32x16_bf16 v[2:17], v[196:199], v[140:143], v[2:17]
	s_waitcnt vmcnt(6)
	v_mfma_f32_32x32x16_bf16 v[18:33], v[200:203], v[112:115], v[18:33]
	v_mfma_f32_32x32x16_bf16 v[2:17], v[200:203], v[144:147], v[2:17]
	s_waitcnt vmcnt(3)
	v_mfma_f32_32x32x16_bf16 v[18:33], v[204:207], v[116:119], v[18:33]
	v_mfma_f32_32x32x16_bf16 v[2:17], v[204:207], v[148:151], v[2:17]
	s_waitcnt vmcnt(0)
	v_mfma_f32_32x32x16_bf16 v[18:33], v[208:211], v[120:123], v[18:33]
	v_mfma_f32_32x32x16_bf16 v[2:17], v[208:211], v[152:155], v[2:17]
	s_cbranch_scc0 .LBB0_1850
	s_nop 8
	v_mul_f32_e32 v44, 0x3f3504f3, v18
	v_cmp_nlt_f32_e64 s[0:1], |v44|, 1.0
	s_and_saveexec_b64 s[2:3], s[0:1]
	s_xor_b64 s[2:3], exec, s[2:3]
	s_cbranch_execz .LBB0_1853
	v_fma_f32 v45, |v44|, s29, v223
	v_fma_f32 v45, |v44|, v45, s20
	v_fma_f32 v45, |v44|, v45, s21
	v_fma_f32 v45, |v44|, v45, s28
	v_fma_f32 v45, |v44|, v45, s33
	v_fma_f32 v45, |v44|, v45, s30
	v_fma_f32 v45, |v44|, v45, |v44|
	v_mul_f32_e32 v46, 0xbfb8aa3b, v45
	v_fma_f32 v47, v45, s31, -v46
	v_rndne_f32_e32 v48, v46
	v_fmac_f32_e32 v47, 0xb2a5705f, v45
	v_sub_f32_e32 v46, v46, v48
	v_add_f32_e32 v46, v46, v47
	v_cvt_i32_f32_e32 v47, v48
	v_exp_f32_e32 v46, v46
	v_cmp_nlt_f32_e32 vcc, s96, v45
	v_ldexp_f32 v46, v46, v47
	s_nop 0
	v_cndmask_b32_e32 v46, 0, v46, vcc
	v_cmp_ngt_f32_e32 vcc, s97, v45
	s_nop 1
	v_cndmask_b32_e32 v45, v224, v46, vcc
	v_sub_f32_e32 v45, 1.0, v45

; DEVI void s5_local_phase(const Params& p) {
;     ...
; #pragma unroll 8
;     for (int s = 0; s < 16; ++s) {
;       const bf16x8 af = *(const bf16x8*)(ua + (size_t)s * 512);
; #pragma unroll
;       for (int nb = 0; nb < 2; ++nb) {
;         const bf16x8 bfr = *(const bf16x8*)(rb + (size_t)nb * 32 * 256 + s * 16);
;         acc[nb] = __builtin_amdgcn_mfma_f32_32x32x16_bf16(af, bfr, acc[nb], 0, 0, 0);
;       }
;     }
.LBB0_2132:
	s_waitcnt vmcnt(0)
	v_lshl_add_u64 v[46:47], v[42:43], 0, v[38:39]
	v_lshl_add_u64 v[62:63], v[44:45], 0, v[38:39]
	v_add_co_u32_e32 v60, vcc, s14, v46
	s_nop 1
	v_addc_co_u32_e32 v61, vcc, 0, v47, vcc
	v_add_co_u32_e32 v46, vcc, s15, v46
	s_nop 1
	v_addc_co_u32_e32 v47, vcc, 0, v47, vcc
	v_add_co_u32_e32 v48, vcc, 0xe8d8000, v62
	s_nop 1
	v_addc_co_u32_e32 v49, vcc, 0, v63, vcc
	v_add_co_u32_e32 v62, vcc, 0xe8dc000, v62
	s_nop 1
	v_addc_co_u32_e32 v63, vcc, 0, v63, vcc
	global_load_dwordx4 v[180:183], v[60:61], off
	global_load_dwordx4 v[92:95], v[48:49], off
	global_load_dwordx4 v[124:127], v[62:63], off
	global_load_dwordx4 v[184:187], v[60:61], off offset:1024
	global_load_dwordx4 v[96:99], v[48:49], off offset:32
	global_load_dwordx4 v[128:131], v[62:63], off offset:32
	global_load_dwordx4 v[188:191], v[60:61], off offset:2048
	global_load_dwordx4 v[100:103], v[48:49], off offset:64
	global_load_dwordx4 v[132:135], v[62:63], off offset:64
	global_load_dwordx4 v[192:195], v[60:61], off offset:3072
	global_load_dwordx4 v[104:107], v[48:49], off offset:96
	global_load_dwordx4 v[136:139], v[62:63], off offset:96
	global_load_dwordx4 v[196:199], v[46:47], off
	global_load_dwordx4 v[108:111], v[48:49], off offset:128
	global_load_dwordx4 v[140:143], v[62:63], off offset:128
	global_load_dwordx4 v[200:203], v[46:47], off offset:1024
	global_load_dwordx4 v[112:115], v[48:49], off offset:160
	global_load_dwordx4 v[144:147], v[62:63], off offset:160
	global_load_dwordx4 v[204:207], v[46:47], off offset:2048
	global_load_dwordx4 v[116:119], v[48:49], off offset:192
	global_load_dwordx4 v[148:151], v[62:63], off offset:192
	global_load_dwordx4 v[208:211], v[46:47], off offset:3072
	global_load_dwordx4 v[120:123], v[48:49], off offset:224
	global_load_dwordx4 v[152:155], v[62:63], off offset:224
	v_lshl_add_u64 v[42:43], v[42:43], 0, s[76:77]
	v_lshl_add_u64 v[44:45], v[44:45], 0, s[82:83]
	s_add_i32 s0, s0, -8
	s_cmp_eq_u32 s0, 0
	s_waitcnt vmcnt(21)
	v_mfma_f32_32x32x16_bf16 v[2:17], v[180:183], v[92:95], v[2:17]
	v_mfma_f32_32x32x16_bf16 v[18:33], v[180:183], v[124:127], v[18:33]
	s_waitcnt vmcnt(18)
	v_mfma_f32_32x32x16_bf16 v[2:17], v[184:187], v[96:99], v[2:17]
	v_mfma_f32_32x32x16_bf16 v[18:33], v[184:187], v[128:131], v[18:33]
	s_waitcnt vmcnt(15)
	v_mfma_f32_32x32x16_bf16 v[2:17], v[188:191], v[100:103], v[2:17]
	v_mfma_f32_32x32x16_bf16 v[18:33], v[188:191], v[132:135], v[18:33]
	s_waitcnt vmcnt(12)
	v_mfma_f32_32x32x16_bf16 v[2:17], v[192:195], v[104:107], v[2:17]
	v_mfma_f32_32x32x16_bf16 v[18:33], v[192:195], v[136:139], v[18:33]
	s_waitcnt vmcnt(9)
	v_mfma_f32_32x32x16_bf16 v[2:17], v[196:199], v[108:111], v[2:17]
	v_mfma_f32_32x32x16_bf16 v[18:33], v[196:199], v[140:143], v[18:33]
	s_waitcnt vmcnt(6)
	v_mfma_f32_32x32x16_bf16 v[2:17], v[200:203], v[112:115], v[2:17]
	v_mfma_f32_32x32x16_bf16 v[18:33], v[200:203], v[144:147], v[18:33]
	s_waitcnt vmcnt(3)
	v_mfma_f32_32x32x16_bf16 v[2:17], v[204:207], v[116:119], v[2:17]
	v_mfma_f32_32x32x16_bf16 v[18:33], v[204:207], v[148:151], v[18:33]
	s_waitcnt vmcnt(0)
	v_mfma_f32_32x32x16_bf16 v[2:17], v[208:211], v[120:123], v[2:17]
	v_mfma_f32_32x32x16_bf16 v[18:33], v[208:211], v[152:155], v[18:33]
	s_cbranch_scc0 .LBB0_2132
; DEVI int crow(int r, int hi) { return (r & 3) + 8 * (r >> 2) + 4 * hi; }
; DEVI void s5_local_phase(const Params& p) {
;     ...
; #pragma unroll
;     for (int nb = 0; nb < 2; ++nb)
; #pragma unroll
;       for (int r = 0; r < 16; ++r) {
;         const int q = cgp * 32 + crow(r, hi);
;         SLOC[((size_t)g * NCH16 + q) * 256 + nq * 64 + nb * 32 + r32] = acc[nb][r];
;       }
	v_or_b32_e32 v42, v51, v50
	v_mul_hi_i32_i24_e32 v41, 0x820, v40
	v_mul_i32_i24_e32 v40, 0x820, v40
	v_ashrrev_i32_e32 v43, 31, v42
	v_or_b32_e32 v48, 1, v42
	v_lshlrev_b32_e32 v0, 2, v0
	v_lshl_add_u64 v[46:47], v[40:41], 0, v[42:43]
	v_ashrrev_i32_e32 v49, 31, v48
	v_lshl_add_u64 v[44:45], v[36:37], 0, v[0:1]
	v_lshlrev_b64 v[46:47], 10, v[46:47]
	v_lshl_add_u64 v[48:49], v[40:41], 0, v[48:49]
	v_lshl_add_u64 v[46:47], v[44:45], 0, v[46:47]
	v_lshlrev_b64 v[48:49], 10, v[48:49]
	global_store_dword v[46:47], v2, off
	v_lshl_add_u64 v[48:49], v[44:45], 0, v[48:49]
	v_or_b32_e32 v2, 2, v42
	global_store_dword v[48:49], v3, off
	v_ashrrev_i32_e32 v3, 31, v2
	v_or_b32_e32 v52, 3, v42
	v_lshl_add_u64 v[2:3], v[40:41], 0, v[2:3]
	v_ashrrev_i32_e32 v53, 31, v52
	v_lshlrev_b64 v[2:3], 10, v[2:3]
	v_lshl_add_u64 v[52:53], v[40:41], 0, v[52:53]
	v_lshl_add_u64 v[2:3], v[44:45], 0, v[2:3]
	v_lshlrev_b64 v[52:53], 10, v[52:53]
	global_store_dword v[2:3], v4, off
	v_lshl_add_u64 v[52:53], v[44:45], 0, v[52:53]
	v_or_b32_e32 v4, 8, v42
	global_store_dword v[52:53], v5, off
	v_ashrrev_i32_e32 v5, 31, v4
	v_or_b32_e32 v54, 9, v42
	v_lshl_add_u64 v[4:5], v[40:41], 0, v[4:5]
	v_ashrrev_i32_e32 v55, 31, v54
	v_lshlrev_b64 v[4:5], 10, v[4:5]
	v_lshl_add_u64 v[54:55], v[40:41], 0, v[54:55]
	v_lshl_add_u64 v[4:5], v[44:45], 0, v[4:5]
	v_lshlrev_b64 v[54:55], 10, v[54:55]
	global_store_dword v[4:5], v6, off
	v_lshl_add_u64 v[54:55], v[44:45], 0, v[54:55]
	v_or_b32_e32 v6, 10, v42
	global_store_dword v[54:55], v7, off
	v_ashrrev_i32_e32 v7, 31, v6
	v_or_b32_e32 v56, 11, v42
	v_lshl_add_u64 v[6:7], v[40:41], 0, v[6:7]
	v_ashrrev_i32_e32 v57, 31, v56
	v_lshlrev_b64 v[6:7], 10, v[6:7]
	v_lshl_add_u64 v[56:57], v[40:41], 0, v[56:57]
	v_lshl_add_u64 v[6:7], v[44:45], 0, v[6:7]
	v_lshlrev_b64 v[56:57], 10, v[56:57]
	global_store_dword v[6:7], v8, off
	v_lshl_add_u64 v[56:57], v[44:45], 0, v[56:57]
	v_or_b32_e32 v8, 16, v42
	global_store_dword v[56:57], v9, off
	v_ashrrev_i32_e32 v9, 31, v8
	v_or_b32_e32 v58, 17, v42
	v_lshl_add_u64 v[8:9], v[40:41], 0, v[8:9]
	v_ashrrev_i32_e32 v59, 31, v58
	v_lshlrev_b64 v[8:9], 10, v[8:9]
	v_lshl_add_u64 v[58:59], v[40:41], 0, v[58:59]
	v_lshl_add_u64 v[8:9], v[44:45], 0, v[8:9]
	v_lshlrev_b64 v[58:59], 10, v[58:59]
	global_store_dword v[8:9], v10, off
	v_lshl_add_u64 v[58:59], v[44:45], 0, v[58:59]
	v_or_b32_e32 v10, 18, v42
	global_store_dword v[58:59], v11, off
	v_ashrrev_i32_e32 v11, 31, v10
	v_or_b32_e32 v60, 19, v42
	v_lshl_add_u64 v[10:11], v[40:41], 0, v[10:11]
	v_ashrrev_i32_e32 v61, 31, v60
	v_lshlrev_b64 v[10:11], 10, v[10:11]
	v_lshl_add_u64 v[60:61], v[40:41], 0, v[60:61]
	v_lshl_add_u64 v[10:11], v[44:45], 0, v[10:11]
	v_lshlrev_b64 v[60:61], 10, v[60:61]
	global_store_dword v[10:11], v12, off
	v_lshl_add_u64 v[60:61], v[44:45], 0, v[60:61]
	v_or_b32_e32 v12, 24, v42
	global_store_dword v[60:61], v13, off
	v_ashrrev_i32_e32 v13, 31, v12
	v_or_b32_e32 v62, 25, v42
	v_lshl_add_u64 v[12:13], v[40:41], 0, v[12:13]
	v_ashrrev_i32_e32 v63, 31, v62
	v_lshlrev_b64 v[12:13], 10, v[12:13]
	v_lshl_add_u64 v[62:63], v[40:41], 0, v[62:63]
	v_lshl_add_u64 v[12:13], v[44:45], 0, v[12:13]
	v_lshlrev_b64 v[62:63], 10, v[62:63]
	global_store_dword v[12:13], v14, off
	v_lshl_add_u64 v[62:63], v[44:45], 0, v[62:63]
	v_or_b32_e32 v14, 26, v42
	v_or_b32_e32 v42, 27, v42
	global_store_dword v[62:63], v15, off
	v_ashrrev_i32_e32 v15, 31, v14
	v_ashrrev_i32_e32 v43, 31, v42
	v_lshl_add_u64 v[14:15], v[40:41], 0, v[14:15]
	v_lshl_add_u64 v[40:41], v[40:41], 0, v[42:43]
	v_lshlrev_b64 v[14:15], 10, v[14:15]
	v_lshlrev_b64 v[40:41], 10, v[40:41]
	v_lshl_add_u64 v[14:15], v[44:45], 0, v[14:15]
	v_lshl_add_u64 v[40:41], v[44:45], 0, v[40:41]
	s_mov_b32 s0, s86
	global_store_dword v[14:15], v16, off
	global_store_dword v[40:41], v17, off
	global_store_dword v[46:47], v18, off offset:128
	global_store_dword v[48:49], v19, off offset:128
	global_store_dword v[2:3], v20, off offset:128
	global_store_dword v[52:53], v21, off offset:128
	global_store_dword v[4:5], v22, off offset:128
	global_store_dword v[54:55], v23, off offset:128
	global_store_dword v[6:7], v24, off offset:128
	global_store_dword v[56:57], v25, off offset:128
	global_store_dword v[8:9], v26, off offset:128
	global_store_dword v[58:59], v27, off offset:128
	global_store_dword v[10:11], v28, off offset:128
	global_store_dword v[60:61], v29, off offset:128
	global_store_dword v[12:13], v30, off offset:128
	global_store_dword v[62:63], v31, off offset:128
	global_store_dword v[14:15], v32, off offset:128
	global_store_dword v[40:41], v33, off offset:128
	s_nop 0
	v_lshl_add_u32 v35, s0, 3, v35
	s_movk_i32 s0, 0x207f
	v_cmp_lt_i32_e32 vcc, s0, v35
	s_or_b64 s[12:13], vcc, s[12:13]
	s_andn2_b64 exec, exec, s[12:13]
	s_cbranch_execnz .LBB0_2127

; DEVI int ltid() { int t = threadIdx.x; asm volatile("" : "+v"(t)); return t; }
; DEVI int v_st(int k, int c) { const int kk = (k & ~0xC) | ((k & 4) << 1) | ((k & 8) >> 1); return ((kk >> 3) * 4 + (c >> 5)) * 512 + ((kk & 7) * 32 + (c & 31)) * 2; }
; DEVI int v_rd_base(int lane) { return ((lane & 3) << 3) | (((lane >> 2) & 3) << 6) | (((lane >> 4) & 1) << 5) | (((lane >> 5) & 1) << 8); }
; #define SLOAD(i, k0) do { sr_[i].vs0 = *reinterpret_cast<const bf16x8*>(&Vh[(long)((k0) + sr) * LDK + sc]); sr_[i].vs1 = *reinterpret_cast<const bf16x8*>(&Vh[(long)((k0) + 32 + sr) * LDK + sc]); \
;     sr_[i].ks0 = *reinterpret_cast<const bf16x8*>(&Kh[(long)((k0) + sr) * LDK + sc]); sr_[i].ks1 = *reinterpret_cast<const bf16x8*>(&Kh[(long)((k0) + 32 + sr) * LDK + sc]); } while (0)
; #define SWRITE(b, i) do { *(bf16x8*)(V_lds + (b) * SHM_V + vst0) = sr_[i].vs0;          \
;     *(bf16x8*)(V_lds + (b) * SHM_V + vst1) = sr_[i].vs1; int kc = sc * 2;               \
;     *(bf16x8*)(K_lds + (b) * SHM_K + KSWZ(sr, kc)) = sr_[i].ks0;                       \
;     *(bf16x8*)(K_lds + (b) * SHM_K + KSWZ(32 + sr, kc)) = sr_[i].ks1; } while (0)
; DEVI void body(const bf16_t* __restrict__ Qb, const bf16_t* __restrict__ Kh, const bf16_t* __restrict__ Vh, bf16_t* __restrict__ Ob, int seq, char* lds) {
;   const int tid = ltid(), wid = tid >> 6, lane = tid & 63, r32 = lane & 31, hi = lane >> 5;
;   char* V_lds = lds; char* K_lds = lds + 2 * SHM_V;
;   float* ws = (float*)(lds + 2 * SHM_V + 2 * SHM_K) + wid * 64; float* li_l = ws; float* al_l = ws + 32;
;   float m_reg = -1e30f, l_reg = 0; f32x16 o[4] = {}; bf16x8 qr[8];
;   const bf16_t* Qw = Qb + (long)(wid * QBLK + r32) * LDQ + hi * 8;
; #pragma unroll
;   for (int d0 = 0; d0 < 8; ++d0) qr[d0] = *reinterpret_cast<const bf16x8*>(Qw + d0 * 16);
;   const int sr = tid >> 4, sc = (tid & 15) * 8, vst0 = v_st(sr, sc), vst1 = v_st(32 + sr, sc);
;   const int vb0 = (int)(uintptr_t)V_lds + v_rd_base(lane);
;   struct { bf16x8 vs0, vs1, ks0, ks1; } sr_[2];
;     ...
;   f32x16 pA0, pA1, pB0, pB1; float mnA, mnB, alA, alB; bf16x8 pa0, pa1, pa2, pa3; const int NT = seq / KVBLK;
;   constexpr int SE = 0, SO = 1;
;   SLOAD(SE, 0); asm volatile("s_waitcnt vmcnt(0)" ::: "memory"); SWRITE(0, SE); __syncthreads();
;   qkt(pA0, pA1, K_lds, qr, r32, hi); partialSM(pA0, pA1, m_reg, mnA, alA);
.LBB0_2666:
	s_and_b64 vcc, exec, s[2:3]
	s_cbranch_vccz .LBB0_2521
	s_ashr_i32 s0, s25, 9
	s_ashr_i32 s1, s0, 31
	s_lshl_b32 s2, s25, 18
	s_and_b32 s15, s2, 0xfc0000
	s_lshl_b64 s[2:3], s[0:1], 24
	s_bfe_u32 s14, s25, 0x10008
	s_or_b32 s1, s2, s15
	s_lshl_b32 s15, s25, 1
	s_lshl_b32 s2, s14, 9
	s_and_b32 s15, s15, 0x180
	s_or_b32 s2, s2, s15
	s_or_b32 s2, s1, s2
	s_lshl_b32 s0, s0, 1
	s_or_b32 s1, s0, s14
	s_lshl_b64 s[14:15], s[2:3], 1
	s_add_u32 s22, s35, s14
	v_mov_b32_e32 v184, v179
	s_addc_u32 s23, s36, s15
	s_mul_i32 s2, s1, 0x410000
	s_mul_hi_i32 s0, s1, 0x410000
	v_ashrrev_i32_e32 v18, 4, v184
	s_add_u32 s16, s37, s2
	v_lshlrev_b32_e32 v24, 3, v184
	v_add_u32_e32 v20, 32, v18
	s_addc_u32 s17, s44, s0
	v_and_b32_e32 v0, 0x78, v24
	v_ashrrev_i32_e32 v19, 31, v18
	v_ashrrev_i32_e32 v21, 31, v20
	s_add_u32 s2, s45, s2
	v_lshlrev_b32_e32 v25, 1, v0
	s_waitcnt vmcnt(11)
	v_lshlrev_b64 v[34:35], 8, v[18:19]
	v_lshlrev_b64 v[14:15], 8, v[20:21]
	s_addc_u32 s3, s46, s0
	v_or_b32_e32 v36, v34, v25
	v_mov_b32_e32 v37, v35
	v_or_b32_e32 v14, v14, v25
	v_lshl_add_u64 v[2:3], s[2:3], 0, v[36:37]
	v_lshl_add_u64 v[6:7], s[2:3], 0, v[14:15]
	global_load_dwordx4 v[2:5], v[2:3], off
	s_nop 0
	global_load_dwordx4 v[6:9], v[6:7], off
	v_lshl_add_u64 v[10:11], s[16:17], 0, v[36:37]
	global_load_dwordx4 v[10:13], v[10:11], off
	v_ashrrev_i32_e32 v181, 6, v184
	v_lshl_add_u64 v[14:15], s[16:17], 0, v[14:15]
	s_waitcnt vmcnt(11)
	v_and_b32_e32 v76, 31, v184
	v_lshlrev_b32_e32 v180, 5, v181
	global_load_dwordx4 v[14:17], v[14:15], off
	v_or_b32_e32 v22, v180, v76
	v_ashrrev_i32_e32 v23, 31, v22
	v_lshlrev_b64 v[22:23], 11, v[22:23]
	v_lshrrev_b32_e32 v0, 1, v184
	v_lshl_add_u64 v[22:23], s[22:23], 0, v[22:23]
	v_and_b32_e32 v0, 16, v0
	v_lshl_add_u64 v[22:23], v[22:23], 0, v[0:1]
	global_load_dwordx4 v[118:121], v[22:23], off
	global_load_dwordx4 v[114:117], v[22:23], off offset:32
	global_load_dwordx4 v[126:129], v[22:23], off offset:64
	global_load_dwordx4 v[122:125], v[22:23], off offset:96
	global_load_dwordx4 v[110:113], v[22:23], off offset:128
	global_load_dwordx4 v[106:109], v[22:23], off offset:160
	global_load_dwordx4 v[102:105], v[22:23], off offset:192
	global_load_dwordx4 v[98:101], v[22:23], off offset:224
	v_and_b32_e32 v21, 0xfffff0, v18
	v_lshlrev_b32_e32 v26, 1, v18
	v_lshrrev_b32_e32 v27, 1, v18
	v_and_b32_e32 v28, 3, v18
	v_and_or_b32 v21, v26, 8, v21
	v_and_or_b32 v26, v27, 4, v28
	v_and_b32_e32 v27, 0xfffff0, v20
	v_lshlrev_b32_e32 v28, 1, v20
	v_and_b32_e32 v19, 0x70, v184
	v_bfe_u32 v24, v24, 5, 2
	v_lshlrev_b32_e32 v18, 8, v18
	v_lshrrev_b32_e32 v21, 1, v21
	v_and_or_b32 v27, v28, 8, v27
	v_bitop3_b32 v18, v25, v18, v19 bitop3:0xde
	v_or_b32_e32 v21, v21, v24
	v_lshrrev_b32_e32 v27, 1, v27
	v_lshlrev_b32_e32 v26, 6, v26
	v_and_b32_e32 v29, 48, v25
	v_add_u32_e32 v192, 16, v18
	v_lshlrev_b32_e32 v18, 9, v21
	v_or_b32_e32 v21, v27, v24
	v_or3_b32 v18, v18, v26, v29
	v_lshlrev_b32_e32 v21, 9, v21
	v_or3_b32 v21, v21, v26, v29
	v_add_u32_e32 v193, 16, v18
	v_lshlrev_b32_e32 v46, 4, v184
	v_add_u32_e32 v194, 16, v21
	s_waitcnt vmcnt(0)
	s_waitcnt vmcnt(18)
	v_lshlrev_b32_e32 v54, 8, v76
	v_and_b32_e32 v55, 0x70, v46
	v_or_b32_e32 v38, 32, v0
	v_bitop3_b32 v38, v38, v54, v55 bitop3:0xde
	v_add_u32_e32 v201, 16, v38
	s_add_i32 s22, 16, 0x10000
	v_and_b32_e32 v57, 0xc0, v46
	v_and_b32_e32 v185, 63, v184
	v_lshlrev_b32_e32 v56, 3, v185
	v_lshlrev_b32_e32 v186, 1, v185
	s_waitcnt vmcnt(11)
	ds_write_b128 v193, v[2:5]
	s_waitcnt vmcnt(10)
	ds_write_b128 v194, v[6:9]
	s_waitcnt vmcnt(9)
	ds_write_b128 v192, v[10:13] offset:32768
	v_lshlrev_b32_e32 v2, 8, v20
	v_bitop3_b32 v2, v25, v2, v19 bitop3:0xde
	v_add_u32_e32 v195, 16, v2
	v_bitop3_b32 v2, v0, v54, v55 bitop3:0xde
	v_add_u32_e32 v196, 16, v2
	v_and_or_b32 v57, v56, 24, v57
	s_waitcnt vmcnt(8)
	ds_write_b128 v195, v[14:17] offset:32768
	s_waitcnt lgkmcnt(0)
	s_barrier
	ds_read_b128 v[2:5], v196 offset:32768
	ds_read_b128 v[18:21], v196 offset:40960
	s_waitcnt vmcnt(7) lgkmcnt(1)
	v_mfma_f32_32x32x16_bf16 v[2:17], v[2:5], v[118:121], 0
	ds_read_b128 v[38:41], v201 offset:32768
	ds_read_b128 v[42:45], v201 offset:40960
	s_mov_b32 s80, s81
	s_mov_b32 s82, s81
	s_mov_b32 s83, s81
	s_mov_b32 s85, s81
	s_mov_b32 s38, s86
	s_mov_b32 s86, s81
	s_waitcnt lgkmcnt(2)
	v_mfma_f32_32x32x16_bf16 v[18:33], v[18:21], v[118:121], 0
	s_mov_b32 s87, s81
	s_mov_b32 s88, s81
	s_mov_b32 s89, s81
	s_mov_b32 s90, s81
	s_mov_b32 s91, s81
	s_mov_b32 s92, s81
	s_mov_b32 s93, s81
	s_waitcnt vmcnt(6) lgkmcnt(1)
	v_mfma_f32_32x32x16_bf16 v[2:17], v[38:41], v[114:117], v[2:17]
	v_or_b32_e32 v38, 64, v0
	v_bitop3_b32 v38, v38, v54, v55 bitop3:0xde
	v_add_u32_e32 v200, 16, v38
	s_mov_b32 s94, s81
	s_mov_b32 s95, s81
	s_cmp_lg_u32 16, -1
	s_mov_b32 s0, 1
	s_waitcnt lgkmcnt(0)
	v_mfma_f32_32x32x16_bf16 v[18:33], v[42:45], v[114:117], v[18:33]
	ds_read_b128 v[38:41], v200 offset:32768
	ds_read_b128 v[42:45], v200 offset:40960
	s_mov_b64 s[76:77], 0x2000
	v_mov_b32_e32 v189, 0
	s_waitcnt vmcnt(5) lgkmcnt(1)
	v_mfma_f32_32x32x16_bf16 v[2:17], v[38:41], v[126:129], v[2:17]
	v_or_b32_e32 v38, 0x60, v0
	v_bitop3_b32 v38, v38, v54, v55 bitop3:0xde
	v_add_u32_e32 v199, 16, v38
	s_waitcnt lgkmcnt(0)
	v_mfma_f32_32x32x16_bf16 v[18:33], v[42:45], v[126:129], v[18:33]
	ds_read_b128 v[38:41], v199 offset:32768
	ds_read_b128 v[42:45], v199 offset:40960
	s_waitcnt vmcnt(4) lgkmcnt(1)
	v_mfma_f32_32x32x16_bf16 v[2:17], v[38:41], v[122:125], v[2:17]
	v_or_b32_e32 v38, 0x80, v0
	v_bitop3_b32 v38, v38, v54, v55 bitop3:0xde
	v_add_u32_e32 v198, 16, v38
	s_waitcnt lgkmcnt(0)
; #define SLOAD(i, k0) do { sr_[i].vs0 = *reinterpret_cast<const bf16x8*>(&Vh[(long)((k0) + sr) * LDK + sc]); sr_[i].vs1 = *reinterpret_cast<const bf16x8*>(&Vh[(long)((k0) + 32 + sr) * LDK + sc]); \
;     sr_[i].ks0 = *reinterpret_cast<const bf16x8*>(&Kh[(long)((k0) + sr) * LDK + sc]); sr_[i].ks1 = *reinterpret_cast<const bf16x8*>(&Kh[(long)((k0) + 32 + sr) * LDK + sc]); } while (0)
; #define SWRITE(b, i) do { *(bf16x8*)(V_lds + (b) * SHM_V + vst0) = sr_[i].vs0;          \
;     *(bf16x8*)(V_lds + (b) * SHM_V + vst1) = sr_[i].vs1; int kc = sc * 2;               \
;     *(bf16x8*)(K_lds + (b) * SHM_K + KSWZ(sr, kc)) = sr_[i].ks0;                       \
;     *(bf16x8*)(K_lds + (b) * SHM_K + KSWZ(32 + sr, kc)) = sr_[i].ks1; } while (0)
; #define SWAIT() asm volatile("s_waitcnt vmcnt(4)" ::: "memory")
; DEVI void partialSM(f32x16& p0, f32x16& p1, float& m_reg, float& mn, float& alpha) {
;   constexpr float C = SCALE * 1.4426950408889634f;
;   float pmax = p0[0];
; #pragma unroll
;   for (int r = 1; r < 16; ++r) pmax = fmaxf(pmax, p0[r]);
; #pragma unroll
;   for (int r = 0; r < 16; ++r) pmax = fmaxf(pmax, p1[r]);
;   { auto rr = __builtin_amdgcn_permlane32_swap(__float_as_uint(pmax), __float_as_uint(pmax), false, false);
;     pmax = fmaxf(__uint_as_float(rr[0]), __uint_as_float(rr[1])); }
;   if (__builtin_expect(__all(pmax - m_reg <= THR / SCALE), 1)) { mn = m_reg; alpha = 1.f; }
;   else { mn = fmaxf(m_reg, pmax); alpha = __builtin_amdgcn_exp2f((m_reg - mn) * C); m_reg = mn; }
;   float mnC = -mn * C;
; #pragma unroll
;   for (int r = 0; r < 16; ++r) p0[r] = fmaf(p0[r], C, mnC);
; #pragma unroll
;   for (int r = 0; r < 16; ++r) p1[r] = fmaf(p1[r], C, mnC);
; #pragma unroll
;   for (int r = 0; r < 16; ++r) p0[r] = __builtin_amdgcn_exp2f(p0[r]);
; }
; DEVI void body(const bf16_t* __restrict__ Qb, const bf16_t* __restrict__ Kh, const bf16_t* __restrict__ Vh, bf16_t* __restrict__ Ob, int seq, char* lds) {
;     ...
;   SLOAD(SE, 0); asm volatile("s_waitcnt vmcnt(0)" ::: "memory"); SWRITE(0, SE); __syncthreads();
;   qkt(pA0, pA1, K_lds, qr, r32, hi); partialSM(pA0, pA1, m_reg, mnA, alA);
;   SLOAD(SO, KVBLK); if (2 < NT) SLOAD(SE, 2 * KVBLK);
;   SWAIT(); SWRITE(1, SO); __syncthreads();
;   for (int j = 1; j + 1 < NT; j += 2) {
	v_mfma_f32_32x32x16_bf16 v[18:33], v[42:45], v[122:125], v[18:33]
	ds_read_b128 v[38:41], v198 offset:32768
	ds_read_b128 v[42:45], v198 offset:40960
	s_waitcnt vmcnt(3) lgkmcnt(1)
	v_mfma_f32_32x32x16_bf16 v[2:17], v[38:41], v[110:113], v[2:17]
	v_or_b32_e32 v38, 0xa0, v0
	v_bitop3_b32 v38, v38, v54, v55 bitop3:0xde
	v_add_u32_e32 v197, 16, v38
	ds_read_b128 v[38:41], v197 offset:32768
	s_waitcnt lgkmcnt(1)
	v_mfma_f32_32x32x16_bf16 v[18:33], v[42:45], v[110:113], v[18:33]
	v_and_b32_e32 v42, 0x3fffffc0, v184
	v_lshl_add_u32 v187, v42, 2, s22
	s_mov_b64 s[22:23], 0x4000
	v_lshl_add_u64 v[50:51], v[36:37], 0, s[22:23]
	s_mov_b64 s[22:23], 0x6000
	v_lshl_add_u64 v[52:53], v[36:37], 0, s[22:23]
	ds_read_b128 v[42:45], v197 offset:40960
	s_waitcnt vmcnt(2) lgkmcnt(1)
	v_mfma_f32_32x32x16_bf16 v[2:17], v[38:41], v[106:109], v[2:17]
	v_lshl_add_u64 v[38:39], s[2:3], 0, v[50:51]
	v_lshl_add_u64 v[46:47], s[2:3], 0, v[52:53]
	v_lshl_add_u64 v[50:51], s[16:17], 0, v[50:51]
	global_load_dwordx4 v[38:41], v[38:39], off
	s_nop 0
	global_load_dwordx4 v[46:49], v[46:47], off
	v_lshl_add_u64 v[52:53], s[16:17], 0, v[52:53]
	global_load_dwordx4 v[66:69], v[50:51], off
	global_load_dwordx4 v[70:73], v[52:53], off
	v_or_b32_e32 v50, 0xc0, v0
	v_bitop3_b32 v50, v50, v54, v55 bitop3:0xde
	v_add_u32_e32 v202, 16, v50
	ds_read_b128 v[50:53], v202 offset:32768
	s_waitcnt lgkmcnt(1)
	v_mfma_f32_32x32x16_bf16 v[18:33], v[42:45], v[106:109], v[18:33]
	v_and_b32_e32 v42, 32, v186
	v_and_b32_e32 v43, 0x100, v56
	v_or3_b32 v77, v57, v42, v43
	ds_read_b128 v[42:45], v202 offset:40960
	s_mov_b32 s23, s84
	s_mov_b32 s84, s81
	s_cselect_b32 s22, 16, 0
	s_waitcnt vmcnt(5) lgkmcnt(1)
	v_mfma_f32_32x32x16_bf16 v[2:17], v[50:53], v[102:105], v[2:17]
	v_or_b32_e32 v50, 0xe0, v0
	v_bitop3_b32 v50, v50, v54, v55 bitop3:0xde
	v_add_u32_e32 v203, 16, v50
	ds_read_b128 v[50:53], v203 offset:32768
	v_add_u32_e32 v191, s22, v77
	v_lshl_add_u32 v188, v76, 2, v187
	s_waitcnt lgkmcnt(1)
	v_mfma_f32_32x32x16_bf16 v[18:33], v[42:45], v[102:105], v[18:33]
	ds_read_b128 v[42:45], v203 offset:40960
	s_waitcnt vmcnt(4) lgkmcnt(1)
	v_mfma_f32_32x32x16_bf16 v[2:17], v[50:53], v[98:101], v[2:17]
	v_mov_b64_e32 v[50:51], s[80:81]
	v_mov_b64_e32 v[52:53], s[82:83]
	v_mov_b64_e32 v[54:55], s[84:85]
	v_mov_b64_e32 v[56:57], s[86:87]
	v_mov_b64_e32 v[58:59], s[88:89]
	v_mov_b64_e32 v[60:61], s[90:91]
	v_mov_b64_e32 v[62:63], s[92:93]
	s_waitcnt lgkmcnt(0)
	v_mfma_f32_32x32x16_bf16 v[18:33], v[42:45], v[98:101], v[18:33]
	s_nop 2
	v_max_f32_e32 v42, v3, v3
	v_max_f32_e32 v43, v2, v2
	v_max_f32_e32 v42, v43, v42
	v_max3_f32 v42, v42, v4, v5
	v_max3_f32 v42, v42, v6, v7
	v_max3_f32 v42, v42, v8, v9
	v_max3_f32 v42, v42, v10, v11
	v_max3_f32 v42, v42, v12, v13
	v_max3_f32 v42, v42, v14, v15
	v_max3_f32 v42, v42, v16, v17
	v_max3_f32 v42, v42, v18, v19
	v_max3_f32 v42, v42, v20, v21
	v_max3_f32 v42, v42, v22, v23
	v_max3_f32 v42, v42, v24, v25
	v_max3_f32 v42, v42, v26, v27
	v_mov_b64_e32 v[64:65], s[94:95]
	s_mov_b32 s86, s38
	v_max3_f32 v42, v42, v28, v29
	s_mov_b64 s[38:39], 0xa000
	s_mov_b64 s[82:83], 0x8000
	v_max3_f32 v78, v42, v30, v31
	v_lshl_add_u64 v[42:43], v[36:37], 0, s[38:39]
	v_lshl_add_u64 v[44:45], s[16:17], 0, v[42:43]
	v_lshl_add_u64 v[36:37], v[36:37], 0, s[82:83]
	v_lshl_add_u64 v[42:43], s[2:3], 0, v[42:43]
	v_lshl_add_u64 v[74:75], s[16:17], 0, v[36:37]
	global_load_dwordx4 v[138:141], v[44:45], off
	global_load_dwordx4 v[130:133], v[74:75], off
	v_lshl_add_u64 v[36:37], s[2:3], 0, v[36:37]
	global_load_dwordx4 v[142:145], v[42:43], off
	global_load_dwordx4 v[134:137], v[36:37], off
	v_max3_f32 v36, v78, v32, v33
	v_mov_b32_e32 v37, v36
	s_nop 1
	v_permlane32_swap_b32_e32 v36, v37
	v_max_f32_e32 v37, v37, v37
	v_max_f32_e32 v36, v36, v36
	v_max_f32_e32 v36, v36, v37
	v_add_f32_e32 v37, 0x7149f2ca, v36
	s_mov_b32 s2, 0x42b504f3
	v_cmp_ge_f32_e32 vcc, s2, v37
	s_cmp_eq_u64 vcc, exec
	v_max_f32_e32 v36, 0xf149f2ca, v36
	s_cselect_b64 vcc, -1, 0
	v_cndmask_b32_e32 v170, v36, v236, vcc
	v_sub_f32_e32 v37, 0xf149f2ca, v36
	v_mul_f32_e32 v36, 0xbe0293ee, v170
	v_fmamk_f32 v2, v2, 0x3e0293ee, v36
	v_exp_f32_e32 v163, v2
	v_fmamk_f32 v2, v3, 0x3e0293ee, v36
	v_exp_f32_e32 v177, v2
	v_fmamk_f32 v2, v4, 0x3e0293ee, v36
	v_exp_f32_e32 v164, v2
	v_fmamk_f32 v2, v5, 0x3e0293ee, v36
	v_exp_f32_e32 v208, v2
	v_fmamk_f32 v2, v6, 0x3e0293ee, v36
	v_exp_f32_e32 v176, v2
	v_fmamk_f32 v2, v7, 0x3e0293ee, v36
	v_exp_f32_e32 v211, v2
	v_fmamk_f32 v2, v8, 0x3e0293ee, v36
	v_exp_f32_e32 v165, v2
	v_fmamk_f32 v2, v9, 0x3e0293ee, v36
	v_exp_f32_e32 v175, v2
	v_fmamk_f32 v2, v10, 0x3e0293ee, v36
	v_exp_f32_e32 v166, v2
	v_fmamk_f32 v2, v11, 0x3e0293ee, v36
	v_mul_f32_e32 v37, 0x3e0293ee, v37
	v_exp_f32_e32 v173, v2
	v_fmamk_f32 v2, v12, 0x3e0293ee, v36
	v_exp_f32_e32 v37, v37
	v_exp_f32_e32 v167, v2
	v_fmamk_f32 v2, v13, 0x3e0293ee, v36
	v_exp_f32_e32 v174, v2
	v_fmamk_f32 v2, v14, 0x3e0293ee, v36
	v_exp_f32_e32 v168, v2
	v_fmamk_f32 v2, v15, 0x3e0293ee, v36
	s_mov_b32 s2, 0x3e0293ee
	v_exp_f32_e32 v171, v2
	v_fmamk_f32 v2, v16, 0x3e0293ee, v36
	s_waitcnt vmcnt(4)
	v_pk_fma_f32 v[148:149], v[32:33], s[2:3], v[36:37] op_sel_hi:[1,0,0]
	v_pk_fma_f32 v[152:153], v[30:31], s[2:3], v[36:37] op_sel_hi:[1,0,0]
	v_pk_fma_f32 v[156:157], v[28:29], s[2:3], v[36:37] op_sel_hi:[1,0,0]
	v_pk_fma_f32 v[146:147], v[26:27], s[2:3], v[36:37] op_sel_hi:[1,0,0]
	v_pk_fma_f32 v[150:151], v[24:25], s[2:3], v[36:37] op_sel_hi:[1,0,0]
	v_pk_fma_f32 v[154:155], v[22:23], s[2:3], v[36:37] op_sel_hi:[1,0,0]
	v_pk_fma_f32 v[158:159], v[20:21], s[2:3], v[36:37] op_sel_hi:[1,0,0]
	v_pk_fma_f32 v[160:161], v[18:19], s[2:3], v[36:37] op_sel_hi:[1,0,0]
	v_exp_f32_e32 v169, v2
	v_mad_i64_i32 v[2:3], s[2:3], s1, v252, v[34:35]
	v_and_b32_e32 v4, 15, v184
	v_fmac_f32_e32 v36, 0x3e0293ee, v17
	v_lshl_or_b32 v2, v4, 4, v2
	s_waitcnt vmcnt(7)
	ds_write_b128 v193, v[38:41] offset:16384
	s_waitcnt vmcnt(6)
	ds_write_b128 v194, v[46:49] offset:16384
	s_waitcnt vmcnt(5)
	ds_write_b128 v192, v[66:69] offset:49152
	s_waitcnt vmcnt(4)
	ds_write_b128 v195, v[70:73] offset:49152
	v_cndmask_b32_e64 v204, v37, 1.0, vcc
	v_exp_f32_e32 v172, v36
	s_addk_i32 s22, 0x4000
	v_lshl_add_u64 v[182:183], s[12:13], 0, v[2:3]
	v_mov_b64_e32 v[34:35], v[50:51]
	v_mov_b64_e32 v[18:19], v[50:51]
	v_mov_b64_e32 v[2:3], v[50:51]
	s_mov_b32 s85, 0xffff
	s_mov_b32 s84, s23
	s_mov_b32 s80, 0x40000
	s_waitcnt lgkmcnt(0)
	s_barrier
	v_readfirstlane_b32 s2, v179
	s_cmpk_lt_u32 s2, 0x100
	s_cbranch_scc1 .Lattn_prio_skip
	s_setprio 1
; DEVI void body(const bf16_t* __restrict__ Qb, const bf16_t* __restrict__ Kh, const bf16_t* __restrict__ Vh, bf16_t* __restrict__ Ob, int seq, char* lds) {
;     ...
;   float m_reg = -1e30f, l_reg = 0; f32x16 o[4] = {}; bf16x8 qr[8];
;     ...
;   for (int j = 1; j + 1 < NT; j += 2) {
.Lattn_prio_skip:
	v_cmp_gt_u32_e64 s[38:39], 32, v185
	v_add_u32_e32 v190, s22, v77
	v_mov_b64_e32 v[36:37], v[52:53]
	v_mov_b64_e32 v[38:39], v[54:55]
	v_mov_b64_e32 v[40:41], v[56:57]
	v_mov_b64_e32 v[42:43], v[58:59]
	v_mov_b64_e32 v[44:45], v[60:61]
	v_mov_b64_e32 v[46:47], v[62:63]
	v_mov_b64_e32 v[48:49], v[64:65]
	v_mov_b64_e32 v[20:21], v[52:53]
	v_mov_b64_e32 v[22:23], v[54:55]
	v_mov_b64_e32 v[24:25], v[56:57]
	v_mov_b64_e32 v[26:27], v[58:59]
	v_mov_b64_e32 v[28:29], v[60:61]
	v_mov_b64_e32 v[30:31], v[62:63]
	v_mov_b64_e32 v[32:33], v[64:65]
	v_mov_b64_e32 v[4:5], v[52:53]
	v_mov_b64_e32 v[6:7], v[54:55]
	v_mov_b64_e32 v[8:9], v[56:57]
	v_mov_b64_e32 v[10:11], v[58:59]
	v_mov_b64_e32 v[12:13], v[60:61]
	v_mov_b64_e32 v[14:15], v[62:63]
	v_mov_b64_e32 v[16:17], v[64:65]

; #define SBAR() __builtin_amdgcn_sched_barrier(0)
; DEVI void finishSM(f32x16& p0, f32x16& p1, float alpha, float& l_reg, bf16x8& pa0, bf16x8& pa1, bf16x8& pa2, bf16x8& pa3) {
; #pragma unroll
;   for (int r = 0; r < 16; ++r) p1[r] = __builtin_amdgcn_exp2f(p1[r]);
;   float ps = 0;
; #pragma unroll
;   for (int r = 0; r < 16; ++r) ps += p0[r];
; #pragma unroll
;   for (int r = 0; r < 16; ++r) ps += p1[r];
;   { auto rr = __builtin_amdgcn_permlane32_swap(__float_as_uint(ps), __float_as_uint(ps), false, false);
;     ps = __uint_as_float(rr[0]) + __uint_as_float(rr[1]); }
;   l_reg = l_reg * alpha + ps;
;     ...
;   PK4(p0, 0, pa0); PK4(p0, 8, pa1); PK4(p1, 0, pa2); PK4(p1, 8, pa3);
;     ...
; }
; DEVI void qkt(f32x16& p0, f32x16& p1, const char* Ks, const bf16x8* qr, int r32, int hi) {
;   p0 = f32x16{}; p1 = f32x16{};
; #pragma unroll
;   for (int d0 = 0; d0 < 8; ++d0) { int cb = (d0 * 16 + hi * 8) * 2;
;     bf16x8 b0 = *reinterpret_cast<const bf16x8*>(Ks + KSWZ(r32, cb));
;     bf16x8 b1 = *reinterpret_cast<const bf16x8*>(Ks + KSWZ(32 + r32, cb));
;     p0 = __builtin_amdgcn_mfma_f32_32x32x16_bf16(b0, qr[d0], p0, 0, 0, 0);
;     p1 = __builtin_amdgcn_mfma_f32_32x32x16_bf16(b1, qr[d0], p1, 0, 0, 0); }
; }
; DEVI void body(const bf16_t* __restrict__ Qb, const bf16_t* __restrict__ Kh, const bf16_t* __restrict__ Vh, bf16_t* __restrict__ Ob, int seq, char* lds) {
;     ...
;   SBAR(); qkt(pB0, pB1, K_lds + SHM_K, qr, r32, hi);
;   finishSM(pA0, pA1, alA, l_reg, pa0, pa1, pa2, pa3); SBAR();
;   pv_d0(o, vb0, pa0, pa1, pa2, pa3); partialSM(pB0, pB1, m_reg, mnB, alB);
.LBB0_2680:
	s_setprio 0
	ds_read_b128 v[66:69], v196 offset:49152
	ds_read_b128 v[70:73], v196 offset:57344
	s_waitcnt lgkmcnt(1)
	v_mfma_f32_32x32x16_bf16 v[82:97], v[66:69], v[118:121], 0
	s_waitcnt lgkmcnt(0)
	v_mfma_f32_32x32x16_bf16 v[66:81], v[70:73], v[118:121], 0
	ds_read_b128 v[118:121], v201 offset:49152
	ds_read_b128 v[130:133], v201 offset:57344
	s_waitcnt lgkmcnt(1)
	v_mfma_f32_32x32x16_bf16 v[82:97], v[118:121], v[114:117], v[82:97]
	s_waitcnt lgkmcnt(0)
	v_mfma_f32_32x32x16_bf16 v[66:81], v[130:133], v[114:117], v[66:81]
	ds_read_b128 v[114:117], v200 offset:49152
	ds_read_b128 v[118:121], v200 offset:57344
	s_waitcnt lgkmcnt(1)
	v_mfma_f32_32x32x16_bf16 v[82:97], v[114:117], v[126:129], v[82:97]
	s_waitcnt lgkmcnt(0)
	v_mfma_f32_32x32x16_bf16 v[66:81], v[118:121], v[126:129], v[66:81]
	ds_read_b128 v[114:117], v199 offset:49152
	ds_read_b128 v[118:121], v199 offset:57344
	s_waitcnt lgkmcnt(1)
	v_mfma_f32_32x32x16_bf16 v[82:97], v[114:117], v[122:125], v[82:97]
	s_waitcnt lgkmcnt(0)
	v_mfma_f32_32x32x16_bf16 v[66:81], v[118:121], v[122:125], v[66:81]
	ds_read_b128 v[114:117], v198 offset:49152
	ds_read_b128 v[118:121], v198 offset:57344
	v_exp_f32_e32 v122, v148
	v_exp_f32_e32 v123, v149
	s_waitcnt lgkmcnt(1)
	v_mfma_f32_32x32x16_bf16 v[82:97], v[114:117], v[110:113], v[82:97]
	s_waitcnt lgkmcnt(0)
	v_mfma_f32_32x32x16_bf16 v[66:81], v[118:121], v[110:113], v[66:81]
	ds_read_b128 v[110:113], v197 offset:49152
	ds_read_b128 v[114:117], v197 offset:57344
	v_exp_f32_e32 v118, v156
	v_exp_f32_e32 v119, v157
	v_exp_f32_e32 v120, v152
	v_exp_f32_e32 v121, v153
	s_waitcnt lgkmcnt(1)
	v_mfma_f32_32x32x16_bf16 v[82:97], v[110:113], v[106:109], v[82:97]
	s_waitcnt lgkmcnt(0)
	v_mfma_f32_32x32x16_bf16 v[66:81], v[114:117], v[106:109], v[66:81]
	ds_read_b128 v[106:109], v202 offset:49152
	ds_read_b128 v[110:113], v202 offset:57344
	v_exp_f32_e32 v114, v150
	v_exp_f32_e32 v115, v151
	v_exp_f32_e32 v116, v146
	v_exp_f32_e32 v117, v147
	s_waitcnt lgkmcnt(1)
	v_mfma_f32_32x32x16_bf16 v[82:97], v[106:109], v[102:105], v[82:97]
	s_waitcnt lgkmcnt(0)
	v_mfma_f32_32x32x16_bf16 v[66:81], v[110:113], v[102:105], v[66:81]
	ds_read_b128 v[102:105], v203 offset:49152
	ds_read_b128 v[106:109], v203 offset:57344
	v_exp_f32_e32 v110, v158
	v_exp_f32_e32 v111, v159
	v_exp_f32_e32 v112, v154
	v_exp_f32_e32 v113, v155
	s_waitcnt lgkmcnt(1)
	v_mfma_f32_32x32x16_bf16 v[82:97], v[102:105], v[98:101], v[82:97]
	s_waitcnt lgkmcnt(0)
	v_mfma_f32_32x32x16_bf16 v[66:81], v[106:109], v[98:101], v[66:81]
	v_add_f32_e32 v98, 0, v163
	v_add_f32_e32 v98, v177, v98
	v_add_f32_e32 v98, v164, v98
	v_add_f32_e32 v98, v208, v98
	v_add_f32_e32 v98, v176, v98
	v_add_f32_e32 v98, v211, v98
	v_add_f32_e32 v98, v165, v98
	v_add_f32_e32 v98, v175, v98
	v_add_f32_e32 v98, v166, v98
	v_add_f32_e32 v98, v173, v98
	v_add_f32_e32 v98, v167, v98
	v_add_f32_e32 v98, v174, v98
	v_exp_f32_e32 v108, v160
	v_add_f32_e32 v98, v168, v98
	v_exp_f32_e32 v109, v161
	v_add_f32_e32 v98, v171, v98
	v_add_f32_e32 v98, v169, v98
	v_add_f32_e32 v98, v172, v98
	v_add_f32_e32 v98, v108, v98
	v_add_f32_e32 v98, v109, v98
	v_add_f32_e32 v98, v110, v98
	v_add_f32_e32 v98, v111, v98
	v_add_f32_e32 v98, v112, v98
	v_add_f32_e32 v98, v113, v98
	v_add_f32_e32 v98, v114, v98
	v_add_f32_e32 v98, v115, v98
	v_add_f32_e32 v98, v116, v98
	v_add_f32_e32 v98, v117, v98
	v_add_f32_e32 v98, v118, v98
	v_add_f32_e32 v98, v119, v98
	v_add_f32_e32 v98, v120, v98
	v_add_f32_e32 v98, v121, v98
	v_add_f32_e32 v98, v122, v98
	v_add_f32_e32 v102, v123, v98
	v_mov_b32_e32 v103, v102
	v_cvt_pk_bf16_f32 v98, v163, v177
	v_cvt_pk_bf16_f32 v99, v164, v208
	v_cvt_pk_bf16_f32 v100, v176, v211
	v_cvt_pk_bf16_f32 v101, v165, v175
	s_nop 1
	v_permlane32_swap_b32_e32 v102, v103
	v_permlane32_swap_b32_e32 v98, v100
	v_permlane32_swap_b32_e32 v99, v101
	v_cvt_pk_bf16_f32 v104, v166, v173
	v_cvt_pk_bf16_f32 v105, v167, v174
	v_cvt_pk_bf16_f32 v106, v168, v171
	v_cvt_pk_bf16_f32 v107, v169, v172
	v_cvt_pk_bf16_f32 v108, v108, v109
	v_cvt_pk_bf16_f32 v109, v110, v111
	v_cvt_pk_bf16_f32 v110, v112, v113
	v_cvt_pk_bf16_f32 v111, v114, v115
	v_cvt_pk_bf16_f32 v112, v116, v117
	v_cvt_pk_bf16_f32 v113, v118, v119
	v_cvt_pk_bf16_f32 v114, v120, v121
	v_cvt_pk_bf16_f32 v115, v122, v123
	s_nop 0
	v_permlane32_swap_b32_e32 v104, v106
	v_permlane32_swap_b32_e32 v105, v107
	v_permlane32_swap_b32_e32 v108, v110
	v_permlane32_swap_b32_e32 v109, v111
	v_permlane32_swap_b32_e32 v112, v114
	v_permlane32_swap_b32_e32 v113, v115
	ds_read_b64_tr_b16 v[116:117], v191 offset:0
	ds_read_b64_tr_b16 v[118:119], v191 offset:0x800
	ds_read_b64_tr_b16 v[120:121], v191 offset:0x1000
	ds_read_b64_tr_b16 v[122:123], v191 offset:0x1800
	ds_read_b64_tr_b16 v[124:125], v191 offset:0x2000
	ds_read_b64_tr_b16 v[126:127], v191 offset:0x2800
	ds_read_b64_tr_b16 v[128:129], v191 offset:0x3000
	ds_read_b64_tr_b16 v[130:131], v191 offset:0x3800
	s_waitcnt lgkmcnt(0)
; #define SBAR() __builtin_amdgcn_sched_barrier(0)
; template <int D0> DEVI void pv_one(f32x16& od, int vb, bf16x8 pa0, bf16x8 pa1, bf16x8 pa2, bf16x8 pa3) {
;   const s16x4 l0 = tr_read<v_rd_off(D0, 0, 0)>(vb), h0 = tr_read<v_rd_off(D0, 0, 1)>(vb), l1 = tr_read<v_rd_off(D0, 1, 0)>(vb), h1 = tr_read<v_rd_off(D0, 1, 1)>(vb);
;   const s16x4 l2 = tr_read<v_rd_off(D0, 2, 0)>(vb), h2 = tr_read<v_rd_off(D0, 2, 1)>(vb), l3 = tr_read<v_rd_off(D0, 3, 0)>(vb), h3 = tr_read<v_rd_off(D0, 3, 1)>(vb);
;   asm volatile("s_waitcnt lgkmcnt(0)" ::: "memory"); SBAR();
;     ...
;   od = __builtin_amdgcn_mfma_f32_32x32x16_bf16(pa0, PK(l0, h0), od, 0, 0, 0);
;   od = __builtin_amdgcn_mfma_f32_32x32x16_bf16(pa1, PK(l1, h1), od, 0, 0, 0);
;   od = __builtin_amdgcn_mfma_f32_32x32x16_bf16(pa2, PK(l2, h2), od, 0, 0, 0);
;   od = __builtin_amdgcn_mfma_f32_32x32x16_bf16(pa3, PK(l3, h3), od, 0, 0, 0);
;     ...
; }
; DEVI void pv_d0(f32x16* o, int vb, bf16x8 pa0, bf16x8 pa1, bf16x8 pa2, bf16x8 pa3) {
;   pv_one<0>(o[0], vb, pa0, pa1, pa2, pa3); pv_one<1>(o[1], vb, pa0, pa1, pa2, pa3); pv_one<2>(o[2], vb, pa0, pa1, pa2, pa3); pv_one<3>(o[3], vb, pa0, pa1, pa2, pa3);
	s_nop 0
	v_mfma_f32_32x32x16_bf16 v[50:65], v[98:101], v[116:119], v[50:65]
	ds_read_b64_tr_b16 v[116:117], v191 offset:0x200
	ds_read_b64_tr_b16 v[118:119], v191 offset:0xa00
	v_mfma_f32_32x32x16_bf16 v[50:65], v[104:107], v[120:123], v[50:65]
	ds_read_b64_tr_b16 v[120:121], v191 offset:0x1200
	ds_read_b64_tr_b16 v[122:123], v191 offset:0x1a00
	v_mfma_f32_32x32x16_bf16 v[50:65], v[108:111], v[124:127], v[50:65]
	ds_read_b64_tr_b16 v[124:125], v191 offset:0x2200
	ds_read_b64_tr_b16 v[126:127], v191 offset:0x2a00
	v_mfma_f32_32x32x16_bf16 v[50:65], v[112:115], v[128:131], v[50:65]
	ds_read_b64_tr_b16 v[128:129], v191 offset:0x3200
	ds_read_b64_tr_b16 v[130:131], v191 offset:0x3a00
	s_waitcnt lgkmcnt(0)
	v_mfma_f32_32x32x16_bf16 v[34:49], v[98:101], v[116:119], v[34:49]
	ds_read_b64_tr_b16 v[116:117], v191 offset:0x400
	ds_read_b64_tr_b16 v[118:119], v191 offset:0xc00
	v_mfma_f32_32x32x16_bf16 v[34:49], v[104:107], v[120:123], v[34:49]
	ds_read_b64_tr_b16 v[120:121], v191 offset:0x1400
	ds_read_b64_tr_b16 v[122:123], v191 offset:0x1c00
	v_mfma_f32_32x32x16_bf16 v[34:49], v[108:111], v[124:127], v[34:49]
	ds_read_b64_tr_b16 v[124:125], v191 offset:0x2400
	ds_read_b64_tr_b16 v[126:127], v191 offset:0x2c00
	v_mfma_f32_32x32x16_bf16 v[34:49], v[112:115], v[128:131], v[34:49]
	ds_read_b64_tr_b16 v[128:129], v191 offset:0x3400
	ds_read_b64_tr_b16 v[130:131], v191 offset:0x3c00
	s_waitcnt lgkmcnt(0)
	v_mfma_f32_32x32x16_bf16 v[18:33], v[98:101], v[116:119], v[18:33]
	ds_read_b64_tr_b16 v[116:117], v191 offset:0x600
	ds_read_b64_tr_b16 v[118:119], v191 offset:0xe00
	v_mfma_f32_32x32x16_bf16 v[18:33], v[104:107], v[120:123], v[18:33]
	ds_read_b64_tr_b16 v[120:121], v191 offset:0x1600
	ds_read_b64_tr_b16 v[122:123], v191 offset:0x1e00
	v_mfma_f32_32x32x16_bf16 v[18:33], v[108:111], v[124:127], v[18:33]
	ds_read_b64_tr_b16 v[124:125], v191 offset:0x2600
	ds_read_b64_tr_b16 v[126:127], v191 offset:0x2e00
	v_mfma_f32_32x32x16_bf16 v[18:33], v[112:115], v[128:131], v[18:33]
	ds_read_b64_tr_b16 v[128:129], v191 offset:0x3600
	ds_read_b64_tr_b16 v[130:131], v191 offset:0x3e00
	s_waitcnt lgkmcnt(0)
	v_mfma_f32_32x32x16_bf16 v[2:17], v[98:101], v[116:119], v[2:17]
	v_max_f32_e32 v98, v83, v83
	v_max_f32_e32 v99, v82, v82
	v_max_f32_e32 v98, v99, v98
	v_max3_f32 v98, v98, v84, v85
	v_max3_f32 v98, v98, v86, v87
	v_max3_f32 v98, v98, v88, v89
	v_max3_f32 v98, v98, v90, v91
	v_max3_f32 v98, v98, v92, v93
	v_max3_f32 v98, v98, v94, v95
	v_mfma_f32_32x32x16_bf16 v[2:17], v[104:107], v[120:123], v[2:17]
	v_max3_f32 v98, v98, v96, v97
	v_max3_f32 v98, v98, v66, v67
	v_max3_f32 v98, v98, v68, v69
	v_max3_f32 v98, v98, v70, v71
	v_max3_f32 v98, v98, v72, v73
	v_max3_f32 v98, v98, v74, v75
	v_max3_f32 v98, v98, v76, v77
	v_max3_f32 v98, v98, v78, v79
	v_mfma_f32_32x32x16_bf16 v[2:17], v[108:111], v[124:127], v[2:17]
	v_max3_f32 v98, v98, v80, v81
	v_mov_b32_e32 v99, v98
	s_nop 1
	v_permlane32_swap_b32_e32 v98, v99
	v_max_f32_e32 v99, v99, v99
	v_max_f32_e32 v98, v98, v98
	v_max_f32_e32 v98, v98, v99
	v_sub_f32_e32 v99, v98, v170
	s_mov_b32 s0, 0x42b504f3
	v_cmp_ge_f32_e32 vcc, s0, v99
	v_max_f32_e32 v99, v170, v170
	v_max_f32_e32 v99, v99, v98
	v_mfma_f32_32x32x16_bf16 v[2:17], v[112:115], v[128:131], v[2:17]
	v_sub_f32_e32 v98, v170, v99
	v_mul_f32_e32 v98, 0x3e0293ee, v98
	v_exp_f32_e32 v98, v98
	s_cmp_eq_u64 vcc, exec
	s_cselect_b64 s[40:41], -1, 0
	v_cndmask_b32_e64 v98, v98, 1.0, s[40:41]
	v_cmp_gt_f32_e32 vcc, 1.0, v98
	s_barrier
	s_cbranch_vccz .LBB0_2684
	s_and_saveexec_b64 s[2:3], s[38:39]
	ds_write_b32 v188, v98 offset:128
	s_or_b64 exec, exec, s[2:3]
	s_waitcnt lgkmcnt(0)
	v_add_u32_e32 v100, v187, v0
	ds_read_b128 v[104:107], v100 offset:224
	ds_read_b128 v[108:111], v100 offset:192
	ds_read_b128 v[112:115], v100 offset:160
	ds_read_b128 v[116:119], v100 offset:128
	s_waitcnt lgkmcnt(3)
	v_pk_mul_f32 v[62:63], v[62:63], v[104:105]
	s_waitcnt lgkmcnt(2)
	v_pk_mul_f32 v[58:59], v[58:59], v[108:109]
	s_waitcnt lgkmcnt(1)
	v_pk_mul_f32 v[54:55], v[54:55], v[112:113]
	v_pk_mul_f32 v[64:65], v[64:65], v[106:107]
	v_pk_mul_f32 v[60:61], v[60:61], v[110:111]
	v_pk_mul_f32 v[56:57], v[56:57], v[114:115]
	s_waitcnt lgkmcnt(0)
	v_pk_mul_f32 v[52:53], v[52:53], v[118:119]
	v_pk_mul_f32 v[50:51], v[50:51], v[116:117]
	v_pk_mul_f32 v[46:47], v[46:47], v[104:105]
	v_pk_mul_f32 v[42:43], v[42:43], v[108:109]
	v_pk_mul_f32 v[38:39], v[38:39], v[112:113]
	v_pk_mul_f32 v[48:49], v[48:49], v[106:107]
	v_pk_mul_f32 v[44:45], v[44:45], v[110:111]
	v_pk_mul_f32 v[40:41], v[40:41], v[114:115]
	v_pk_mul_f32 v[36:37], v[36:37], v[118:119]
	v_pk_mul_f32 v[34:35], v[34:35], v[116:117]
	v_pk_mul_f32 v[30:31], v[30:31], v[104:105]
	v_pk_mul_f32 v[26:27], v[26:27], v[108:109]
	v_pk_mul_f32 v[22:23], v[22:23], v[112:113]
	v_pk_mul_f32 v[32:33], v[32:33], v[106:107]
	v_pk_mul_f32 v[28:29], v[28:29], v[110:111]
	v_pk_mul_f32 v[24:25], v[24:25], v[114:115]
	v_pk_mul_f32 v[20:21], v[20:21], v[118:119]
	v_pk_mul_f32 v[18:19], v[18:19], v[116:117]
	v_pk_mul_f32 v[14:15], v[14:15], v[104:105]
	v_pk_mul_f32 v[10:11], v[10:11], v[108:109]
	v_pk_mul_f32 v[6:7], v[6:7], v[112:113]
	v_pk_mul_f32 v[16:17], v[16:17], v[106:107]
	v_pk_mul_f32 v[12:13], v[12:13], v[110:111]
	v_pk_mul_f32 v[8:9], v[8:9], v[114:115]
	v_pk_mul_f32 v[4:5], v[4:5], v[118:119]
	v_pk_mul_f32 v[2:3], v[2:3], v[116:117]
